# GEMM K-loops: full 32-MFMA snake per phase (chains adjacent, runs of 4 share the A-fragment operand), mid-phase s_setprio toggle removed
# speedup vs baseline: 1.0199x; 1.0071x over previous
.LBB0_261:
	s_add_u32 s0, s76, 0xfff80080
	s_addc_u32 s1, s77, -1
	s_and_b64 s[84:85], s[84:85], exec
	s_cselect_b32 vcc_hi, s22, s1
	s_cselect_b32 vcc_lo, s23, s0
	s_cselect_b32 s85, s49, s58
	s_cselect_b32 s84, s57, s51
	s_add_i32 s0, 0, 0x10000
	s_add_i32 s1, 0, 0x14000
	v_add_u32_e32 v158, s0, v176
	v_add_u32_e32 v174, s1, v176
	ds_read_b128 v[146:149], v158
	ds_read_b128 v[150:153], v158 offset:1024
	ds_read_b128 v[154:157], v158 offset:2048
	ds_read_b128 v[158:161], v158 offset:3072
	ds_read_b128 v[162:165], v174
	ds_read_b128 v[166:169], v174 offset:1024
	ds_read_b128 v[170:173], v174 offset:2048
	ds_read_b128 v[178:181], v174 offset:3072
	v_lshl_add_u64 v[174:175], s[76:77], 0, v[138:139]
	s_add_i32 m0, s21, 0xc000
	ds_read_b128 v[182:185], v177
	ds_read_b128 v[186:189], v177 offset:1024
	ds_read_b128 v[190:193], v177 offset:2048
	ds_read_b128 v[204:207], v177 offset:3072
	ds_read_b128 v[208:211], v177 offset:4096
	ds_read_b128 v[212:215], v177 offset:5120
	ds_read_b128 v[216:219], v177 offset:6144
	ds_read_b128 v[220:223], v177 offset:7168
	global_load_lds_dwordx4 v[174:175], off
	v_lshl_add_u64 v[174:175], s[76:77], 0, v[140:141]
	s_add_i32 m0, s21, 0xe000
	s_nop 0
	global_load_lds_dwordx4 v[174:175], off
	s_waitcnt vmcnt(8)
	s_waitcnt lgkmcnt(0)
	s_barrier
	s_setprio 1
	s_waitcnt lgkmcnt(0)
	v_mfma_f32_16x16x32_bf16 v[126:129], v[146:149], v[182:185], v[126:129]
	v_mfma_f32_16x16x32_bf16 v[126:129], v[150:153], v[186:189], v[126:129]
	v_mfma_f32_16x16x32_bf16 v[122:125], v[158:161], v[186:189], v[122:125]
	v_mfma_f32_16x16x32_bf16 v[122:125], v[154:157], v[182:185], v[122:125]
	v_mfma_f32_16x16x32_bf16 v[118:121], v[162:165], v[182:185], v[118:121]
	v_mfma_f32_16x16x32_bf16 v[118:121], v[166:169], v[186:189], v[118:121]
	v_mfma_f32_16x16x32_bf16 v[114:117], v[178:181], v[186:189], v[114:117]
	v_mfma_f32_16x16x32_bf16 v[114:117], v[170:173], v[182:185], v[114:117]
	v_mfma_f32_16x16x32_bf16 v[98:101], v[170:173], v[190:193], v[98:101]
	v_mfma_f32_16x16x32_bf16 v[98:101], v[178:181], v[204:207], v[98:101]
	v_mfma_f32_16x16x32_bf16 v[102:105], v[166:169], v[204:207], v[102:105]
	v_mfma_f32_16x16x32_bf16 v[102:105], v[162:165], v[190:193], v[102:105]
	v_mfma_f32_16x16x32_bf16 v[106:109], v[154:157], v[190:193], v[106:109]
	v_mfma_f32_16x16x32_bf16 v[106:109], v[158:161], v[204:207], v[106:109]
	v_mfma_f32_16x16x32_bf16 v[110:113], v[150:153], v[204:207], v[110:113]
	v_mfma_f32_16x16x32_bf16 v[110:113], v[146:149], v[190:193], v[110:113]
	v_mfma_f32_16x16x32_bf16 v[94:97], v[146:149], v[208:211], v[94:97]
	v_mfma_f32_16x16x32_bf16 v[94:97], v[150:153], v[212:215], v[94:97]
	v_mfma_f32_16x16x32_bf16 v[90:93], v[158:161], v[212:215], v[90:93]
	v_mfma_f32_16x16x32_bf16 v[90:93], v[154:157], v[208:211], v[90:93]
	v_mfma_f32_16x16x32_bf16 v[86:89], v[162:165], v[208:211], v[86:89]
	v_mfma_f32_16x16x32_bf16 v[86:89], v[166:169], v[212:215], v[86:89]
	v_mfma_f32_16x16x32_bf16 v[82:85], v[178:181], v[212:215], v[82:85]
	v_mfma_f32_16x16x32_bf16 v[82:85], v[170:173], v[208:211], v[82:85]
	v_mfma_f32_16x16x32_bf16 v[66:69], v[170:173], v[216:219], v[66:69]
	v_mfma_f32_16x16x32_bf16 v[66:69], v[178:181], v[220:223], v[66:69]
	v_mfma_f32_16x16x32_bf16 v[70:73], v[166:169], v[220:223], v[70:73]
	v_mfma_f32_16x16x32_bf16 v[70:73], v[162:165], v[216:219], v[70:73]
	v_mfma_f32_16x16x32_bf16 v[74:77], v[154:157], v[216:219], v[74:77]
	v_mfma_f32_16x16x32_bf16 v[74:77], v[158:161], v[220:223], v[74:77]
	v_mfma_f32_16x16x32_bf16 v[78:81], v[150:153], v[220:223], v[78:81]
	v_mfma_f32_16x16x32_bf16 v[78:81], v[146:149], v[216:219], v[78:81]
	s_setprio 0
	s_barrier
	s_add_i32 s0, s0, s20
	v_lshl_add_u64 v[174:175], s[84:85], 0, v[132:133]
	s_mov_b32 m0, s0
	ds_read_b128 v[182:185], v177 offset:16384
	ds_read_b128 v[186:189], v177 offset:17408
	ds_read_b128 v[190:193], v177 offset:18432
	ds_read_b128 v[204:207], v177 offset:19456
	ds_read_b128 v[208:211], v177 offset:20480
	ds_read_b128 v[212:215], v177 offset:21504
	ds_read_b128 v[216:219], v177 offset:22528
	ds_read_b128 v[220:223], v177 offset:23552
	global_load_lds_dwordx4 v[174:175], off
	s_add_i32 m0, s0, 0x2000
	s_add_u32 s94, s84, 0x80000
	v_lshl_add_u64 v[224:225], s[84:85], 0, v[130:131]
	s_addc_u32 s95, s85, 0
	s_add_i32 s0, s1, s20
	global_load_lds_dwordx4 v[224:225], off
	v_lshl_add_u64 v[226:227], s[94:95], 0, v[132:133]
	s_mov_b32 m0, s0
	v_lshl_add_u64 v[228:229], vcc, 0, v[130:131]
	global_load_lds_dwordx4 v[226:227], off
	v_lshl_add_u64 v[226:227], s[94:95], 0, v[130:131]
	s_add_i32 m0, s0, 0x2000
	s_nop 0
	global_load_lds_dwordx4 v[226:227], off
	v_lshl_add_u64 v[226:227], vcc, 0, v[132:133]
	s_mov_b32 m0, s21
	s_nop 0
	global_load_lds_dwordx4 v[226:227], off
	s_mov_b32 m0, s26
	s_nop 0
	global_load_lds_dwordx4 v[228:229], off
	s_waitcnt vmcnt(8)
	s_waitcnt lgkmcnt(0)
	s_barrier
	s_setprio 1
	s_waitcnt lgkmcnt(0)
	v_mfma_f32_16x16x32_bf16 v[62:65], v[146:149], v[182:185], v[62:65]
	v_mfma_f32_16x16x32_bf16 v[62:65], v[150:153], v[186:189], v[62:65]
	v_mfma_f32_16x16x32_bf16 v[58:61], v[158:161], v[186:189], v[58:61]
	v_mfma_f32_16x16x32_bf16 v[58:61], v[154:157], v[182:185], v[58:61]
	v_mfma_f32_16x16x32_bf16 v[54:57], v[162:165], v[182:185], v[54:57]
	v_mfma_f32_16x16x32_bf16 v[54:57], v[166:169], v[186:189], v[54:57]
	v_mfma_f32_16x16x32_bf16 v[50:53], v[178:181], v[186:189], v[50:53]
	v_mfma_f32_16x16x32_bf16 v[50:53], v[170:173], v[182:185], v[50:53]
	v_mfma_f32_16x16x32_bf16 v[34:37], v[170:173], v[190:193], v[34:37]
	v_mfma_f32_16x16x32_bf16 v[34:37], v[178:181], v[204:207], v[34:37]
	v_mfma_f32_16x16x32_bf16 v[38:41], v[166:169], v[204:207], v[38:41]
	v_mfma_f32_16x16x32_bf16 v[38:41], v[162:165], v[190:193], v[38:41]
	v_mfma_f32_16x16x32_bf16 v[42:45], v[154:157], v[190:193], v[42:45]
	v_mfma_f32_16x16x32_bf16 v[42:45], v[158:161], v[204:207], v[42:45]
	v_mfma_f32_16x16x32_bf16 v[46:49], v[150:153], v[204:207], v[46:49]
	v_mfma_f32_16x16x32_bf16 v[46:49], v[146:149], v[190:193], v[46:49]
	v_mfma_f32_16x16x32_bf16 v[30:33], v[146:149], v[208:211], v[30:33]
	v_mfma_f32_16x16x32_bf16 v[30:33], v[150:153], v[212:215], v[30:33]
	v_mfma_f32_16x16x32_bf16 v[26:29], v[158:161], v[212:215], v[26:29]
	v_mfma_f32_16x16x32_bf16 v[26:29], v[154:157], v[208:211], v[26:29]
	v_mfma_f32_16x16x32_bf16 v[22:25], v[162:165], v[208:211], v[22:25]
	v_mfma_f32_16x16x32_bf16 v[22:25], v[166:169], v[212:215], v[22:25]
	v_mfma_f32_16x16x32_bf16 v[18:21], v[178:181], v[212:215], v[18:21]
	v_mfma_f32_16x16x32_bf16 v[18:21], v[170:173], v[208:211], v[18:21]
	v_mfma_f32_16x16x32_bf16 v[2:5], v[170:173], v[216:219], v[2:5]
	v_mfma_f32_16x16x32_bf16 v[2:5], v[178:181], v[220:223], v[2:5]
	v_mfma_f32_16x16x32_bf16 v[6:9], v[166:169], v[220:223], v[6:9]
	v_mfma_f32_16x16x32_bf16 v[6:9], v[162:165], v[216:219], v[6:9]
	v_mfma_f32_16x16x32_bf16 v[10:13], v[154:157], v[216:219], v[10:13]
	v_mfma_f32_16x16x32_bf16 v[10:13], v[158:161], v[220:223], v[10:13]
	v_mfma_f32_16x16x32_bf16 v[14:17], v[150:153], v[220:223], v[14:17]
	v_mfma_f32_16x16x32_bf16 v[14:17], v[146:149], v[216:219], v[14:17]
	s_setprio 0
	s_barrier
	s_add_i32 s0, 0, 0x18000
	s_add_i32 s1, 0, 0x1c000
	v_add_u32_e32 v158, s0, v176
	v_add_u32_e32 v178, s1, v176
	ds_read_b128 v[146:149], v158
	ds_read_b128 v[150:153], v158 offset:1024
	ds_read_b128 v[154:157], v158 offset:2048
	ds_read_b128 v[158:161], v158 offset:3072
	ds_read_b128 v[162:165], v178
	ds_read_b128 v[166:169], v178 offset:1024
	ds_read_b128 v[170:173], v178 offset:2048
	ds_read_b128 v[178:181], v178 offset:3072
	s_add_u32 s94, vcc_lo, 0x80000
	s_addc_u32 s95, vcc_hi, 0
	s_mov_b32 m0, s27
	v_lshl_add_u64 v[230:231], s[94:95], 0, v[132:133]
	ds_read_b128 v[182:185], v177 offset:32768
	ds_read_b128 v[186:189], v177 offset:33792
	ds_read_b128 v[190:193], v177 offset:34816
	ds_read_b128 v[204:207], v177 offset:35840
	ds_read_b128 v[208:211], v177 offset:36864
	ds_read_b128 v[212:215], v177 offset:37888
	ds_read_b128 v[216:219], v177 offset:38912
	ds_read_b128 v[220:223], v177 offset:39936
	global_load_lds_dwordx4 v[230:231], off
	v_lshl_add_u64 v[230:231], s[94:95], 0, v[130:131]
	s_mov_b32 m0, s29
	s_nop 0
	global_load_lds_dwordx4 v[230:231], off
	s_waitcnt vmcnt(8)
	s_waitcnt lgkmcnt(0)
	s_barrier
	s_setprio 1
	s_waitcnt lgkmcnt(0)
	v_mfma_f32_16x16x32_bf16 v[126:129], v[146:149], v[182:185], v[126:129]
	v_mfma_f32_16x16x32_bf16 v[126:129], v[150:153], v[186:189], v[126:129]
	v_mfma_f32_16x16x32_bf16 v[122:125], v[158:161], v[186:189], v[122:125]
	v_mfma_f32_16x16x32_bf16 v[122:125], v[154:157], v[182:185], v[122:125]
	v_mfma_f32_16x16x32_bf16 v[118:121], v[162:165], v[182:185], v[118:121]
	v_mfma_f32_16x16x32_bf16 v[118:121], v[166:169], v[186:189], v[118:121]
	v_mfma_f32_16x16x32_bf16 v[114:117], v[178:181], v[186:189], v[114:117]
	v_mfma_f32_16x16x32_bf16 v[114:117], v[170:173], v[182:185], v[114:117]
	v_mfma_f32_16x16x32_bf16 v[98:101], v[170:173], v[190:193], v[98:101]
	v_mfma_f32_16x16x32_bf16 v[98:101], v[178:181], v[204:207], v[98:101]
	v_mfma_f32_16x16x32_bf16 v[102:105], v[166:169], v[204:207], v[102:105]
	v_mfma_f32_16x16x32_bf16 v[102:105], v[162:165], v[190:193], v[102:105]
	v_mfma_f32_16x16x32_bf16 v[106:109], v[154:157], v[190:193], v[106:109]
	v_mfma_f32_16x16x32_bf16 v[106:109], v[158:161], v[204:207], v[106:109]
	v_mfma_f32_16x16x32_bf16 v[110:113], v[150:153], v[204:207], v[110:113]
	v_mfma_f32_16x16x32_bf16 v[110:113], v[146:149], v[190:193], v[110:113]
	v_mfma_f32_16x16x32_bf16 v[94:97], v[146:149], v[208:211], v[94:97]
	v_mfma_f32_16x16x32_bf16 v[94:97], v[150:153], v[212:215], v[94:97]
	v_mfma_f32_16x16x32_bf16 v[90:93], v[158:161], v[212:215], v[90:93]
	v_mfma_f32_16x16x32_bf16 v[90:93], v[154:157], v[208:211], v[90:93]
	v_mfma_f32_16x16x32_bf16 v[86:89], v[162:165], v[208:211], v[86:89]
	v_mfma_f32_16x16x32_bf16 v[86:89], v[166:169], v[212:215], v[86:89]
	v_mfma_f32_16x16x32_bf16 v[82:85], v[178:181], v[212:215], v[82:85]
	v_mfma_f32_16x16x32_bf16 v[82:85], v[170:173], v[208:211], v[82:85]
	v_mfma_f32_16x16x32_bf16 v[66:69], v[170:173], v[216:219], v[66:69]
	v_mfma_f32_16x16x32_bf16 v[66:69], v[178:181], v[220:223], v[66:69]
	v_mfma_f32_16x16x32_bf16 v[70:73], v[166:169], v[220:223], v[70:73]
	v_mfma_f32_16x16x32_bf16 v[70:73], v[162:165], v[216:219], v[70:73]
	v_mfma_f32_16x16x32_bf16 v[74:77], v[154:157], v[216:219], v[74:77]
	v_mfma_f32_16x16x32_bf16 v[74:77], v[158:161], v[220:223], v[74:77]
	v_mfma_f32_16x16x32_bf16 v[78:81], v[150:153], v[220:223], v[78:81]
	v_mfma_f32_16x16x32_bf16 v[78:81], v[146:149], v[216:219], v[78:81]
	s_setprio 0
	s_barrier
	s_add_i32 s0, s0, s20
	v_lshl_add_u64 v[174:175], v[174:175], 0, s[82:83]
	s_mov_b32 m0, s0
	ds_read_b128 v[182:185], v177 offset:49152
	ds_read_b128 v[186:189], v177 offset:50176
	ds_read_b128 v[190:193], v177 offset:51200
	ds_read_b128 v[204:207], v177 offset:52224
	ds_read_b128 v[208:211], v177 offset:53248
	ds_read_b128 v[212:215], v177 offset:54272
	ds_read_b128 v[216:219], v177 offset:55296
	ds_read_b128 v[220:223], v177 offset:56320
	global_load_lds_dwordx4 v[174:175], off
	s_add_i32 m0, s0, 0x2000
	s_add_u32 s84, s84, 0x80080
	v_lshl_add_u64 v[174:175], v[224:225], 0, s[82:83]
	s_addc_u32 s85, s85, 0
	s_add_i32 s0, s1, s20
	global_load_lds_dwordx4 v[174:175], off
	v_lshl_add_u64 v[174:175], s[84:85], 0, v[132:133]
	s_mov_b32 m0, s0
	s_nop 0
	global_load_lds_dwordx4 v[174:175], off
	v_lshl_add_u64 v[174:175], s[84:85], 0, v[130:131]
	s_add_i32 m0, s0, 0x2000
	s_nop 0
	global_load_lds_dwordx4 v[174:175], off
	v_lshl_add_u64 v[174:175], v[226:227], 0, s[82:83]
	s_mov_b32 m0, s40
	s_nop 0
	global_load_lds_dwordx4 v[174:175], off
	v_lshl_add_u64 v[174:175], v[228:229], 0, s[82:83]
	s_mov_b32 m0, s41
	s_nop 0
	global_load_lds_dwordx4 v[174:175], off
	s_waitcnt vmcnt(8)
	s_waitcnt lgkmcnt(0)
	s_barrier
	s_setprio 1
	s_waitcnt lgkmcnt(0)
	v_mfma_f32_16x16x32_bf16 v[62:65], v[146:149], v[182:185], v[62:65]
	v_mfma_f32_16x16x32_bf16 v[62:65], v[150:153], v[186:189], v[62:65]
	v_mfma_f32_16x16x32_bf16 v[58:61], v[158:161], v[186:189], v[58:61]
	v_mfma_f32_16x16x32_bf16 v[58:61], v[154:157], v[182:185], v[58:61]
	v_mfma_f32_16x16x32_bf16 v[54:57], v[162:165], v[182:185], v[54:57]
	v_mfma_f32_16x16x32_bf16 v[54:57], v[166:169], v[186:189], v[54:57]
	v_mfma_f32_16x16x32_bf16 v[50:53], v[178:181], v[186:189], v[50:53]
	v_mfma_f32_16x16x32_bf16 v[50:53], v[170:173], v[182:185], v[50:53]
	v_mfma_f32_16x16x32_bf16 v[34:37], v[170:173], v[190:193], v[34:37]
	v_mfma_f32_16x16x32_bf16 v[34:37], v[178:181], v[204:207], v[34:37]
	v_mfma_f32_16x16x32_bf16 v[38:41], v[166:169], v[204:207], v[38:41]
	v_mfma_f32_16x16x32_bf16 v[38:41], v[162:165], v[190:193], v[38:41]
	v_mfma_f32_16x16x32_bf16 v[42:45], v[154:157], v[190:193], v[42:45]
	v_mfma_f32_16x16x32_bf16 v[42:45], v[158:161], v[204:207], v[42:45]
	v_mfma_f32_16x16x32_bf16 v[46:49], v[150:153], v[204:207], v[46:49]
	v_mfma_f32_16x16x32_bf16 v[46:49], v[146:149], v[190:193], v[46:49]
	v_mfma_f32_16x16x32_bf16 v[30:33], v[146:149], v[208:211], v[30:33]
	v_mfma_f32_16x16x32_bf16 v[30:33], v[150:153], v[212:215], v[30:33]
	v_mfma_f32_16x16x32_bf16 v[26:29], v[158:161], v[212:215], v[26:29]
	v_mfma_f32_16x16x32_bf16 v[26:29], v[154:157], v[208:211], v[26:29]
	v_mfma_f32_16x16x32_bf16 v[22:25], v[162:165], v[208:211], v[22:25]
	v_mfma_f32_16x16x32_bf16 v[22:25], v[166:169], v[212:215], v[22:25]
	v_mfma_f32_16x16x32_bf16 v[18:21], v[178:181], v[212:215], v[18:21]
	v_mfma_f32_16x16x32_bf16 v[18:21], v[170:173], v[208:211], v[18:21]
	v_mfma_f32_16x16x32_bf16 v[2:5], v[170:173], v[216:219], v[2:5]
	v_mfma_f32_16x16x32_bf16 v[2:5], v[178:181], v[220:223], v[2:5]
	v_mfma_f32_16x16x32_bf16 v[6:9], v[166:169], v[220:223], v[6:9]
	v_mfma_f32_16x16x32_bf16 v[6:9], v[162:165], v[216:219], v[6:9]
	v_mfma_f32_16x16x32_bf16 v[10:13], v[154:157], v[216:219], v[10:13]
	v_mfma_f32_16x16x32_bf16 v[10:13], v[158:161], v[220:223], v[10:13]
	v_mfma_f32_16x16x32_bf16 v[14:17], v[150:153], v[220:223], v[14:17]
	v_mfma_f32_16x16x32_bf16 v[14:17], v[146:149], v[216:219], v[14:17]
	s_setprio 0
	s_barrier
	s_add_i32 s65, s65, 2
	s_add_u32 s76, s76, 0x100
	s_addc_u32 s77, s77, 0
	s_add_u32 s51, s51, 0x100
	s_addc_u32 s58, s58, 0
	s_cmp_gt_u32 s65, 29
	s_cbranch_scc1 .LBB0_264

.LBB0_285:
	s_add_u32 s0, s76, 0xfff80080
	s_addc_u32 s1, s77, -1
	s_and_b64 s[70:71], s[70:71], exec
	s_cselect_b32 vcc_hi, s21, s1
	s_cselect_b32 vcc_lo, s22, s0
	s_cselect_b32 s71, s23, s41
	s_cselect_b32 s70, s39, s7
	s_add_i32 s0, 0, 0x10000
	s_add_i32 s1, 0, 0x14000
	v_add_u32_e32 v146, s0, v1
	v_add_u32_e32 v174, s1, v1
	ds_read_b128 v[134:137], v146
	ds_read_b128 v[138:141], v146 offset:1024
	ds_read_b128 v[142:145], v146 offset:2048
	ds_read_b128 v[146:149], v146 offset:3072
	ds_read_b128 v[150:153], v174
	ds_read_b128 v[154:157], v174 offset:1024
	ds_read_b128 v[158:161], v174 offset:2048
	ds_read_b128 v[174:177], v174 offset:3072
	v_lshl_add_u64 v[220:221], s[76:77], 0, v[170:171]
	s_add_i32 m0, s67, 0xc000
	ds_read_b128 v[178:181], v222
	ds_read_b128 v[182:185], v222 offset:1024
	ds_read_b128 v[186:189], v222 offset:2048
	ds_read_b128 v[190:193], v222 offset:3072
	ds_read_b128 v[204:207], v222 offset:4096
	ds_read_b128 v[208:211], v222 offset:5120
	ds_read_b128 v[212:215], v222 offset:6144
	ds_read_b128 v[216:219], v222 offset:7168
	global_load_lds_dwordx4 v[220:221], off
	v_lshl_add_u64 v[220:221], s[76:77], 0, v[172:173]
	s_add_i32 m0, s67, 0xe000
	s_nop 0
	global_load_lds_dwordx4 v[220:221], off
	s_waitcnt vmcnt(8)
	s_waitcnt lgkmcnt(0)
	s_barrier
	s_setprio 1
	s_waitcnt lgkmcnt(0)
	v_mfma_f32_16x16x32_bf16 v[126:129], v[134:137], v[178:181], v[126:129]
	v_mfma_f32_16x16x32_bf16 v[126:129], v[138:141], v[182:185], v[126:129]
	v_mfma_f32_16x16x32_bf16 v[122:125], v[146:149], v[182:185], v[122:125]
	v_mfma_f32_16x16x32_bf16 v[122:125], v[142:145], v[178:181], v[122:125]
	v_mfma_f32_16x16x32_bf16 v[118:121], v[150:153], v[178:181], v[118:121]
	v_mfma_f32_16x16x32_bf16 v[118:121], v[154:157], v[182:185], v[118:121]
	v_mfma_f32_16x16x32_bf16 v[114:117], v[174:177], v[182:185], v[114:117]
	v_mfma_f32_16x16x32_bf16 v[114:117], v[158:161], v[178:181], v[114:117]
	v_mfma_f32_16x16x32_bf16 v[98:101], v[158:161], v[186:189], v[98:101]
	v_mfma_f32_16x16x32_bf16 v[98:101], v[174:177], v[190:193], v[98:101]
	v_mfma_f32_16x16x32_bf16 v[102:105], v[154:157], v[190:193], v[102:105]
	v_mfma_f32_16x16x32_bf16 v[102:105], v[150:153], v[186:189], v[102:105]
	v_mfma_f32_16x16x32_bf16 v[106:109], v[142:145], v[186:189], v[106:109]
	v_mfma_f32_16x16x32_bf16 v[106:109], v[146:149], v[190:193], v[106:109]
	v_mfma_f32_16x16x32_bf16 v[110:113], v[138:141], v[190:193], v[110:113]
	v_mfma_f32_16x16x32_bf16 v[110:113], v[134:137], v[186:189], v[110:113]
	v_mfma_f32_16x16x32_bf16 v[94:97], v[134:137], v[204:207], v[94:97]
	v_mfma_f32_16x16x32_bf16 v[94:97], v[138:141], v[208:211], v[94:97]
	v_mfma_f32_16x16x32_bf16 v[90:93], v[146:149], v[208:211], v[90:93]
	v_mfma_f32_16x16x32_bf16 v[90:93], v[142:145], v[204:207], v[90:93]
	v_mfma_f32_16x16x32_bf16 v[86:89], v[150:153], v[204:207], v[86:89]
	v_mfma_f32_16x16x32_bf16 v[86:89], v[154:157], v[208:211], v[86:89]
	v_mfma_f32_16x16x32_bf16 v[82:85], v[174:177], v[208:211], v[82:85]
	v_mfma_f32_16x16x32_bf16 v[82:85], v[158:161], v[204:207], v[82:85]
	v_mfma_f32_16x16x32_bf16 v[66:69], v[158:161], v[212:215], v[66:69]
	v_mfma_f32_16x16x32_bf16 v[66:69], v[174:177], v[216:219], v[66:69]
	v_mfma_f32_16x16x32_bf16 v[70:73], v[154:157], v[216:219], v[70:73]
	v_mfma_f32_16x16x32_bf16 v[70:73], v[150:153], v[212:215], v[70:73]
	v_mfma_f32_16x16x32_bf16 v[74:77], v[142:145], v[212:215], v[74:77]
	v_mfma_f32_16x16x32_bf16 v[74:77], v[146:149], v[216:219], v[74:77]
	v_mfma_f32_16x16x32_bf16 v[78:81], v[138:141], v[216:219], v[78:81]
	v_mfma_f32_16x16x32_bf16 v[78:81], v[134:137], v[212:215], v[78:81]
	s_setprio 0
	s_barrier
	s_add_i32 s0, s0, s54
	v_lshl_add_u64 v[220:221], s[70:71], 0, v[164:165]
	s_mov_b32 m0, s0
	ds_read_b128 v[178:181], v222 offset:16384
	ds_read_b128 v[182:185], v222 offset:17408
	ds_read_b128 v[186:189], v222 offset:18432
	ds_read_b128 v[190:193], v222 offset:19456
	ds_read_b128 v[204:207], v222 offset:20480
	ds_read_b128 v[208:211], v222 offset:21504
	ds_read_b128 v[212:215], v222 offset:22528
	ds_read_b128 v[216:219], v222 offset:23552
	global_load_lds_dwordx4 v[220:221], off
	s_add_i32 m0, s0, 0x2000
	s_add_u32 s44, s70, 0x80000
	v_lshl_add_u64 v[224:225], s[70:71], 0, v[162:163]
	s_addc_u32 s45, s71, 0
	s_add_i32 s0, s1, s54
	global_load_lds_dwordx4 v[224:225], off
	v_lshl_add_u64 v[226:227], s[44:45], 0, v[164:165]
	s_mov_b32 m0, s0
	v_lshl_add_u64 v[228:229], vcc, 0, v[162:163]
	global_load_lds_dwordx4 v[226:227], off
	v_lshl_add_u64 v[226:227], s[44:45], 0, v[162:163]
	s_add_i32 m0, s0, 0x2000
	s_nop 0
	global_load_lds_dwordx4 v[226:227], off
	v_lshl_add_u64 v[226:227], vcc, 0, v[164:165]
	s_mov_b32 m0, s67
	s_nop 0
	global_load_lds_dwordx4 v[226:227], off
	s_mov_b32 m0, s68
	s_nop 0
	global_load_lds_dwordx4 v[228:229], off
	s_waitcnt vmcnt(8)
	s_waitcnt lgkmcnt(0)
	s_barrier
	s_setprio 1
	s_waitcnt lgkmcnt(0)
	v_mfma_f32_16x16x32_bf16 v[62:65], v[134:137], v[178:181], v[62:65]
	v_mfma_f32_16x16x32_bf16 v[62:65], v[138:141], v[182:185], v[62:65]
	v_mfma_f32_16x16x32_bf16 v[58:61], v[146:149], v[182:185], v[58:61]
	v_mfma_f32_16x16x32_bf16 v[58:61], v[142:145], v[178:181], v[58:61]
	v_mfma_f32_16x16x32_bf16 v[54:57], v[150:153], v[178:181], v[54:57]
	v_mfma_f32_16x16x32_bf16 v[54:57], v[154:157], v[182:185], v[54:57]
	v_mfma_f32_16x16x32_bf16 v[50:53], v[174:177], v[182:185], v[50:53]
	v_mfma_f32_16x16x32_bf16 v[50:53], v[158:161], v[178:181], v[50:53]
	v_mfma_f32_16x16x32_bf16 v[34:37], v[158:161], v[186:189], v[34:37]
	v_mfma_f32_16x16x32_bf16 v[34:37], v[174:177], v[190:193], v[34:37]
	v_mfma_f32_16x16x32_bf16 v[38:41], v[154:157], v[190:193], v[38:41]
	v_mfma_f32_16x16x32_bf16 v[38:41], v[150:153], v[186:189], v[38:41]
	v_mfma_f32_16x16x32_bf16 v[42:45], v[142:145], v[186:189], v[42:45]
	v_mfma_f32_16x16x32_bf16 v[42:45], v[146:149], v[190:193], v[42:45]
	v_mfma_f32_16x16x32_bf16 v[46:49], v[138:141], v[190:193], v[46:49]
	v_mfma_f32_16x16x32_bf16 v[46:49], v[134:137], v[186:189], v[46:49]
	v_mfma_f32_16x16x32_bf16 v[30:33], v[134:137], v[204:207], v[30:33]
	v_mfma_f32_16x16x32_bf16 v[30:33], v[138:141], v[208:211], v[30:33]
	v_mfma_f32_16x16x32_bf16 v[26:29], v[146:149], v[208:211], v[26:29]
	v_mfma_f32_16x16x32_bf16 v[26:29], v[142:145], v[204:207], v[26:29]
	v_mfma_f32_16x16x32_bf16 v[22:25], v[150:153], v[204:207], v[22:25]
	v_mfma_f32_16x16x32_bf16 v[22:25], v[154:157], v[208:211], v[22:25]
	v_mfma_f32_16x16x32_bf16 v[18:21], v[174:177], v[208:211], v[18:21]
	v_mfma_f32_16x16x32_bf16 v[18:21], v[158:161], v[204:207], v[18:21]
	v_mfma_f32_16x16x32_bf16 v[2:5], v[158:161], v[212:215], v[2:5]
	v_mfma_f32_16x16x32_bf16 v[2:5], v[174:177], v[216:219], v[2:5]
	v_mfma_f32_16x16x32_bf16 v[6:9], v[154:157], v[216:219], v[6:9]
	v_mfma_f32_16x16x32_bf16 v[6:9], v[150:153], v[212:215], v[6:9]
	v_mfma_f32_16x16x32_bf16 v[10:13], v[142:145], v[212:215], v[10:13]
	v_mfma_f32_16x16x32_bf16 v[10:13], v[146:149], v[216:219], v[10:13]
	v_mfma_f32_16x16x32_bf16 v[14:17], v[138:141], v[216:219], v[14:17]
	v_mfma_f32_16x16x32_bf16 v[14:17], v[134:137], v[212:215], v[14:17]
	s_setprio 0
	s_barrier
	s_add_i32 s0, 0, 0x18000
	s_add_i32 s1, 0, 0x1c000
	v_add_u32_e32 v146, s0, v1
	v_add_u32_e32 v174, s1, v1
	ds_read_b128 v[134:137], v146
	ds_read_b128 v[138:141], v146 offset:1024
	ds_read_b128 v[142:145], v146 offset:2048
	ds_read_b128 v[146:149], v146 offset:3072
	ds_read_b128 v[150:153], v174
	ds_read_b128 v[154:157], v174 offset:1024
	ds_read_b128 v[158:161], v174 offset:2048
	ds_read_b128 v[174:177], v174 offset:3072
	s_add_u32 s44, vcc_lo, 0x80000
	s_addc_u32 s45, vcc_hi, 0
	s_mov_b32 m0, s8
	v_lshl_add_u64 v[230:231], s[44:45], 0, v[164:165]
	ds_read_b128 v[178:181], v222 offset:32768
	ds_read_b128 v[182:185], v222 offset:33792
	ds_read_b128 v[186:189], v222 offset:34816
	ds_read_b128 v[190:193], v222 offset:35840
	ds_read_b128 v[204:207], v222 offset:36864
	ds_read_b128 v[208:211], v222 offset:37888
	ds_read_b128 v[212:215], v222 offset:38912
	ds_read_b128 v[216:219], v222 offset:39936
	global_load_lds_dwordx4 v[230:231], off
	v_lshl_add_u64 v[230:231], s[44:45], 0, v[162:163]
	s_mov_b32 m0, s9
	s_nop 0
	global_load_lds_dwordx4 v[230:231], off
	s_waitcnt vmcnt(8)
	s_waitcnt lgkmcnt(0)
	s_barrier
	s_setprio 1
	s_waitcnt lgkmcnt(0)
	v_mfma_f32_16x16x32_bf16 v[126:129], v[134:137], v[178:181], v[126:129]
	v_mfma_f32_16x16x32_bf16 v[126:129], v[138:141], v[182:185], v[126:129]
	v_mfma_f32_16x16x32_bf16 v[122:125], v[146:149], v[182:185], v[122:125]
	v_mfma_f32_16x16x32_bf16 v[122:125], v[142:145], v[178:181], v[122:125]
	v_mfma_f32_16x16x32_bf16 v[118:121], v[150:153], v[178:181], v[118:121]
	v_mfma_f32_16x16x32_bf16 v[118:121], v[154:157], v[182:185], v[118:121]
	v_mfma_f32_16x16x32_bf16 v[114:117], v[174:177], v[182:185], v[114:117]
	v_mfma_f32_16x16x32_bf16 v[114:117], v[158:161], v[178:181], v[114:117]
	v_mfma_f32_16x16x32_bf16 v[98:101], v[158:161], v[186:189], v[98:101]
	v_mfma_f32_16x16x32_bf16 v[98:101], v[174:177], v[190:193], v[98:101]
	v_mfma_f32_16x16x32_bf16 v[102:105], v[154:157], v[190:193], v[102:105]
	v_mfma_f32_16x16x32_bf16 v[102:105], v[150:153], v[186:189], v[102:105]
	v_mfma_f32_16x16x32_bf16 v[106:109], v[142:145], v[186:189], v[106:109]
	v_mfma_f32_16x16x32_bf16 v[106:109], v[146:149], v[190:193], v[106:109]
	v_mfma_f32_16x16x32_bf16 v[110:113], v[138:141], v[190:193], v[110:113]
	v_mfma_f32_16x16x32_bf16 v[110:113], v[134:137], v[186:189], v[110:113]
	v_mfma_f32_16x16x32_bf16 v[94:97], v[134:137], v[204:207], v[94:97]
	v_mfma_f32_16x16x32_bf16 v[94:97], v[138:141], v[208:211], v[94:97]
	v_mfma_f32_16x16x32_bf16 v[90:93], v[146:149], v[208:211], v[90:93]
	v_mfma_f32_16x16x32_bf16 v[90:93], v[142:145], v[204:207], v[90:93]
	v_mfma_f32_16x16x32_bf16 v[86:89], v[150:153], v[204:207], v[86:89]
	v_mfma_f32_16x16x32_bf16 v[86:89], v[154:157], v[208:211], v[86:89]
	v_mfma_f32_16x16x32_bf16 v[82:85], v[174:177], v[208:211], v[82:85]
	v_mfma_f32_16x16x32_bf16 v[82:85], v[158:161], v[204:207], v[82:85]
	v_mfma_f32_16x16x32_bf16 v[66:69], v[158:161], v[212:215], v[66:69]
	v_mfma_f32_16x16x32_bf16 v[66:69], v[174:177], v[216:219], v[66:69]
	v_mfma_f32_16x16x32_bf16 v[70:73], v[154:157], v[216:219], v[70:73]
	v_mfma_f32_16x16x32_bf16 v[70:73], v[150:153], v[212:215], v[70:73]
	v_mfma_f32_16x16x32_bf16 v[74:77], v[142:145], v[212:215], v[74:77]
	v_mfma_f32_16x16x32_bf16 v[74:77], v[146:149], v[216:219], v[74:77]
	v_mfma_f32_16x16x32_bf16 v[78:81], v[138:141], v[216:219], v[78:81]
	v_mfma_f32_16x16x32_bf16 v[78:81], v[134:137], v[212:215], v[78:81]
	s_setprio 0
	s_barrier
	s_add_i32 s0, s0, s54
	v_lshl_add_u64 v[220:221], v[220:221], 0, s[82:83]
	s_mov_b32 m0, s0
	ds_read_b128 v[178:181], v222 offset:49152
	ds_read_b128 v[182:185], v222 offset:50176
	ds_read_b128 v[186:189], v222 offset:51200
	ds_read_b128 v[190:193], v222 offset:52224
	ds_read_b128 v[204:207], v222 offset:53248
	ds_read_b128 v[208:211], v222 offset:54272
	ds_read_b128 v[212:215], v222 offset:55296
	ds_read_b128 v[216:219], v222 offset:56320
	global_load_lds_dwordx4 v[220:221], off
	s_add_i32 m0, s0, 0x2000
	s_add_u32 s44, s70, 0x80080
	v_lshl_add_u64 v[220:221], v[224:225], 0, s[82:83]
	s_addc_u32 s45, s71, 0
	s_add_i32 s0, s1, s54
	global_load_lds_dwordx4 v[220:221], off
	v_lshl_add_u64 v[220:221], s[44:45], 0, v[164:165]
	s_mov_b32 m0, s0
	s_nop 0
	global_load_lds_dwordx4 v[220:221], off
	v_lshl_add_u64 v[220:221], s[44:45], 0, v[162:163]
	s_add_i32 m0, s0, 0x2000
	s_nop 0
	global_load_lds_dwordx4 v[220:221], off
	v_lshl_add_u64 v[220:221], v[226:227], 0, s[82:83]
	s_mov_b32 m0, s27
	s_nop 0
	global_load_lds_dwordx4 v[220:221], off
	v_lshl_add_u64 v[220:221], v[228:229], 0, s[82:83]
	s_mov_b32 m0, s26
	s_nop 0
	global_load_lds_dwordx4 v[220:221], off
	s_waitcnt vmcnt(8)
	s_waitcnt lgkmcnt(0)
	s_barrier
	s_setprio 1
	s_waitcnt lgkmcnt(0)
	v_mfma_f32_16x16x32_bf16 v[62:65], v[134:137], v[178:181], v[62:65]
	v_mfma_f32_16x16x32_bf16 v[62:65], v[138:141], v[182:185], v[62:65]
	v_mfma_f32_16x16x32_bf16 v[58:61], v[146:149], v[182:185], v[58:61]
	v_mfma_f32_16x16x32_bf16 v[58:61], v[142:145], v[178:181], v[58:61]
	v_mfma_f32_16x16x32_bf16 v[54:57], v[150:153], v[178:181], v[54:57]
	v_mfma_f32_16x16x32_bf16 v[54:57], v[154:157], v[182:185], v[54:57]
	v_mfma_f32_16x16x32_bf16 v[50:53], v[174:177], v[182:185], v[50:53]
	v_mfma_f32_16x16x32_bf16 v[50:53], v[158:161], v[178:181], v[50:53]
	v_mfma_f32_16x16x32_bf16 v[34:37], v[158:161], v[186:189], v[34:37]
	v_mfma_f32_16x16x32_bf16 v[34:37], v[174:177], v[190:193], v[34:37]
	v_mfma_f32_16x16x32_bf16 v[38:41], v[154:157], v[190:193], v[38:41]
	v_mfma_f32_16x16x32_bf16 v[38:41], v[150:153], v[186:189], v[38:41]
	v_mfma_f32_16x16x32_bf16 v[42:45], v[142:145], v[186:189], v[42:45]
	v_mfma_f32_16x16x32_bf16 v[42:45], v[146:149], v[190:193], v[42:45]
	v_mfma_f32_16x16x32_bf16 v[46:49], v[138:141], v[190:193], v[46:49]
	v_mfma_f32_16x16x32_bf16 v[46:49], v[134:137], v[186:189], v[46:49]
	v_mfma_f32_16x16x32_bf16 v[30:33], v[134:137], v[204:207], v[30:33]
	v_mfma_f32_16x16x32_bf16 v[30:33], v[138:141], v[208:211], v[30:33]
	v_mfma_f32_16x16x32_bf16 v[26:29], v[146:149], v[208:211], v[26:29]
	v_mfma_f32_16x16x32_bf16 v[26:29], v[142:145], v[204:207], v[26:29]
	v_mfma_f32_16x16x32_bf16 v[22:25], v[150:153], v[204:207], v[22:25]
	v_mfma_f32_16x16x32_bf16 v[22:25], v[154:157], v[208:211], v[22:25]
	v_mfma_f32_16x16x32_bf16 v[18:21], v[174:177], v[208:211], v[18:21]
	v_mfma_f32_16x16x32_bf16 v[18:21], v[158:161], v[204:207], v[18:21]
	v_mfma_f32_16x16x32_bf16 v[2:5], v[158:161], v[212:215], v[2:5]
	v_mfma_f32_16x16x32_bf16 v[2:5], v[174:177], v[216:219], v[2:5]
	v_mfma_f32_16x16x32_bf16 v[6:9], v[154:157], v[216:219], v[6:9]
	v_mfma_f32_16x16x32_bf16 v[6:9], v[150:153], v[212:215], v[6:9]
	v_mfma_f32_16x16x32_bf16 v[10:13], v[142:145], v[212:215], v[10:13]
	v_mfma_f32_16x16x32_bf16 v[10:13], v[146:149], v[216:219], v[10:13]
	v_mfma_f32_16x16x32_bf16 v[14:17], v[138:141], v[216:219], v[14:17]
	v_mfma_f32_16x16x32_bf16 v[14:17], v[134:137], v[212:215], v[14:17]
	s_setprio 0
	s_barrier
	s_add_i32 s43, s43, 2
	s_add_u32 s76, s76, 0x100
	s_addc_u32 s77, s77, 0
	s_add_u32 s7, s7, 0x100
	s_addc_u32 s41, s41, 0
	s_cmp_gt_u32 s43, 29
	s_cbranch_scc1 .LBB0_288

.LBB0_509:
	s_add_u32 s90, s76, 0x100
	s_addc_u32 s91, s77, 0
	s_and_b64 s[0:1], s[70:71], exec
	s_cselect_b32 vcc_hi, s22, s91
	s_cselect_b32 vcc_lo, s23, s90
	s_cselect_b32 s71, s41, s53
	s_cselect_b32 s70, s44, s51
	s_add_i32 s0, 0, 0x10000
	s_add_i32 s18, 0, 0x14000
	v_add_u32_e32 v114, s0, v1
	v_add_u32_e32 v154, s18, v1
	ds_read_b128 v[78:81], v114
	ds_read_b128 v[90:93], v114 offset:1024
	ds_read_b128 v[102:105], v114 offset:2048
	ds_read_b128 v[114:117], v114 offset:3072
	ds_read_b128 v[126:129], v154
	ds_read_b128 v[134:137], v154 offset:1024
	ds_read_b128 v[142:145], v154 offset:2048
	ds_read_b128 v[154:157], v154 offset:3072
	v_lshl_add_u64 v[218:219], s[76:77], 0, v[210:211]
	s_add_i32 m0, s29, 0xc000
	ds_read_b128 v[158:161], v237
	ds_read_b128 v[162:165], v237 offset:1024
	ds_read_b128 v[166:169], v237 offset:2048
	ds_read_b128 v[178:181], v237 offset:3072
	ds_read_b128 v[182:185], v237 offset:4096
	ds_read_b128 v[186:189], v237 offset:5120
	ds_read_b128 v[190:193], v237 offset:6144
	ds_read_b128 v[214:217], v237 offset:7168
	global_load_lds_dwordx4 v[218:219], off
	v_lshl_add_u64 v[218:219], s[76:77], 0, v[212:213]
	s_add_i32 m0, s29, 0xe000
	s_nop 0
	global_load_lds_dwordx4 v[218:219], off
	s_waitcnt vmcnt(8)
	s_waitcnt lgkmcnt(0)
	s_barrier
	s_setprio 1
	s_waitcnt lgkmcnt(0)
	v_mfma_f32_16x16x32_bf16 v[174:177], v[78:81], v[158:161], v[174:177]
	v_mfma_f32_16x16x32_bf16 v[174:177], v[90:93], v[162:165], v[174:177]
	v_mfma_f32_16x16x32_bf16 v[170:173], v[114:117], v[162:165], v[170:173]
	v_mfma_f32_16x16x32_bf16 v[170:173], v[102:105], v[158:161], v[170:173]
	v_mfma_f32_16x16x32_bf16 v[150:153], v[126:129], v[158:161], v[150:153]
	v_mfma_f32_16x16x32_bf16 v[150:153], v[134:137], v[162:165], v[150:153]
	v_mfma_f32_16x16x32_bf16 v[146:149], v[154:157], v[162:165], v[146:149]
	v_mfma_f32_16x16x32_bf16 v[146:149], v[142:145], v[158:161], v[146:149]
	v_mfma_f32_16x16x32_bf16 v[118:121], v[142:145], v[166:169], v[118:121]
	v_mfma_f32_16x16x32_bf16 v[118:121], v[154:157], v[178:181], v[118:121]
	v_mfma_f32_16x16x32_bf16 v[122:125], v[134:137], v[178:181], v[122:125]
	v_mfma_f32_16x16x32_bf16 v[122:125], v[126:129], v[166:169], v[122:125]
	v_mfma_f32_16x16x32_bf16 v[130:133], v[102:105], v[166:169], v[130:133]
	v_mfma_f32_16x16x32_bf16 v[130:133], v[114:117], v[178:181], v[130:133]
	v_mfma_f32_16x16x32_bf16 v[138:141], v[90:93], v[178:181], v[138:141]
	v_mfma_f32_16x16x32_bf16 v[138:141], v[78:81], v[166:169], v[138:141]
	v_mfma_f32_16x16x32_bf16 v[110:113], v[78:81], v[182:185], v[110:113]
	v_mfma_f32_16x16x32_bf16 v[110:113], v[90:93], v[186:189], v[110:113]
	v_mfma_f32_16x16x32_bf16 v[106:109], v[114:117], v[186:189], v[106:109]
	v_mfma_f32_16x16x32_bf16 v[106:109], v[102:105], v[182:185], v[106:109]
	v_mfma_f32_16x16x32_bf16 v[98:101], v[126:129], v[182:185], v[98:101]
	v_mfma_f32_16x16x32_bf16 v[98:101], v[134:137], v[186:189], v[98:101]
	v_mfma_f32_16x16x32_bf16 v[94:97], v[154:157], v[186:189], v[94:97]
	v_mfma_f32_16x16x32_bf16 v[94:97], v[142:145], v[182:185], v[94:97]
	v_mfma_f32_16x16x32_bf16 v[66:69], v[142:145], v[190:193], v[66:69]
	v_mfma_f32_16x16x32_bf16 v[66:69], v[154:157], v[214:217], v[66:69]
	v_mfma_f32_16x16x32_bf16 v[74:77], v[134:137], v[214:217], v[74:77]
	v_mfma_f32_16x16x32_bf16 v[74:77], v[126:129], v[190:193], v[74:77]
	v_mfma_f32_16x16x32_bf16 v[82:85], v[102:105], v[190:193], v[82:85]
	v_mfma_f32_16x16x32_bf16 v[82:85], v[114:117], v[214:217], v[82:85]
	v_mfma_f32_16x16x32_bf16 v[86:89], v[90:93], v[214:217], v[86:89]
	v_mfma_f32_16x16x32_bf16 v[86:89], v[78:81], v[190:193], v[86:89]
	s_setprio 0
	s_barrier
	s_add_i32 s0, s0, s28
	v_lshl_add_u64 v[218:219], s[70:71], 0, v[194:195]
	s_mov_b32 m0, s0
	ds_read_b128 v[158:161], v237 offset:16384
	ds_read_b128 v[162:165], v237 offset:17408
	ds_read_b128 v[166:169], v237 offset:18432
	ds_read_b128 v[178:181], v237 offset:19456
	ds_read_b128 v[182:185], v237 offset:20480
	ds_read_b128 v[186:189], v237 offset:21504
	ds_read_b128 v[190:193], v237 offset:22528
	ds_read_b128 v[214:217], v237 offset:23552
	global_load_lds_dwordx4 v[218:219], off
	s_add_i32 m0, s0, 0x2000
	s_add_u32 s0, s70, 0x80000
	v_lshl_add_u64 v[220:221], s[70:71], 0, v[204:205]
	s_addc_u32 s1, s71, 0
	s_add_i32 s18, s18, s28
	global_load_lds_dwordx4 v[220:221], off
	v_lshl_add_u64 v[222:223], s[0:1], 0, v[194:195]
	s_mov_b32 m0, s18
	v_lshl_add_u64 v[224:225], vcc, 0, v[204:205]
	global_load_lds_dwordx4 v[222:223], off
	v_lshl_add_u64 v[222:223], s[0:1], 0, v[204:205]
	s_add_i32 m0, s18, 0x2000
	s_nop 0
	global_load_lds_dwordx4 v[222:223], off
	v_lshl_add_u64 v[222:223], vcc, 0, v[194:195]
	s_mov_b32 m0, s29
	s_nop 0
	global_load_lds_dwordx4 v[222:223], off
	s_mov_b32 m0, s31
	s_nop 0
	global_load_lds_dwordx4 v[224:225], off
	s_waitcnt vmcnt(8)
	s_waitcnt lgkmcnt(0)
	s_barrier
	s_setprio 1
	s_waitcnt lgkmcnt(0)
	v_mfma_f32_16x16x32_bf16 v[62:65], v[78:81], v[158:161], v[62:65]
	v_mfma_f32_16x16x32_bf16 v[62:65], v[90:93], v[162:165], v[62:65]
	v_mfma_f32_16x16x32_bf16 v[58:61], v[114:117], v[162:165], v[58:61]
	v_mfma_f32_16x16x32_bf16 v[58:61], v[102:105], v[158:161], v[58:61]
	v_mfma_f32_16x16x32_bf16 v[54:57], v[126:129], v[158:161], v[54:57]
	v_mfma_f32_16x16x32_bf16 v[54:57], v[134:137], v[162:165], v[54:57]
	v_mfma_f32_16x16x32_bf16 v[50:53], v[154:157], v[162:165], v[50:53]
	v_mfma_f32_16x16x32_bf16 v[50:53], v[142:145], v[158:161], v[50:53]
	v_mfma_f32_16x16x32_bf16 v[34:37], v[142:145], v[166:169], v[34:37]
	v_mfma_f32_16x16x32_bf16 v[34:37], v[154:157], v[178:181], v[34:37]
	v_mfma_f32_16x16x32_bf16 v[38:41], v[134:137], v[178:181], v[38:41]
	v_mfma_f32_16x16x32_bf16 v[38:41], v[126:129], v[166:169], v[38:41]
	v_mfma_f32_16x16x32_bf16 v[42:45], v[102:105], v[166:169], v[42:45]
	v_mfma_f32_16x16x32_bf16 v[42:45], v[114:117], v[178:181], v[42:45]
	v_mfma_f32_16x16x32_bf16 v[46:49], v[90:93], v[178:181], v[46:49]
	v_mfma_f32_16x16x32_bf16 v[46:49], v[78:81], v[166:169], v[46:49]
	v_mfma_f32_16x16x32_bf16 v[30:33], v[78:81], v[182:185], v[30:33]
	v_mfma_f32_16x16x32_bf16 v[30:33], v[90:93], v[186:189], v[30:33]
	v_mfma_f32_16x16x32_bf16 v[26:29], v[114:117], v[186:189], v[26:29]
	v_mfma_f32_16x16x32_bf16 v[26:29], v[102:105], v[182:185], v[26:29]
	v_mfma_f32_16x16x32_bf16 v[22:25], v[126:129], v[182:185], v[22:25]
	v_mfma_f32_16x16x32_bf16 v[22:25], v[134:137], v[186:189], v[22:25]
	v_mfma_f32_16x16x32_bf16 v[18:21], v[154:157], v[186:189], v[18:21]
	v_mfma_f32_16x16x32_bf16 v[18:21], v[142:145], v[182:185], v[18:21]
	v_mfma_f32_16x16x32_bf16 v[2:5], v[142:145], v[190:193], v[2:5]
	v_mfma_f32_16x16x32_bf16 v[2:5], v[154:157], v[214:217], v[2:5]
	v_mfma_f32_16x16x32_bf16 v[6:9], v[134:137], v[214:217], v[6:9]
	v_mfma_f32_16x16x32_bf16 v[6:9], v[126:129], v[190:193], v[6:9]
	v_mfma_f32_16x16x32_bf16 v[10:13], v[102:105], v[190:193], v[10:13]
	v_mfma_f32_16x16x32_bf16 v[10:13], v[114:117], v[214:217], v[10:13]
	v_mfma_f32_16x16x32_bf16 v[14:17], v[90:93], v[214:217], v[14:17]
	v_mfma_f32_16x16x32_bf16 v[14:17], v[78:81], v[190:193], v[14:17]
	s_setprio 0
	s_barrier
	s_add_i32 s18, 0, 0x18000
	s_add_i32 s19, 0, 0x1c000
	v_add_u32_e32 v114, s18, v1
	v_add_u32_e32 v154, s19, v1
	ds_read_b128 v[78:81], v114
	ds_read_b128 v[90:93], v114 offset:1024
	ds_read_b128 v[102:105], v114 offset:2048
	ds_read_b128 v[114:117], v114 offset:3072
	ds_read_b128 v[126:129], v154
	ds_read_b128 v[134:137], v154 offset:1024
	ds_read_b128 v[142:145], v154 offset:2048
	ds_read_b128 v[154:157], v154 offset:3072
	s_add_u32 s0, vcc_lo, 0x80000
	s_addc_u32 s1, vcc_hi, 0
	s_mov_b32 m0, s33
	v_lshl_add_u64 v[226:227], s[0:1], 0, v[194:195]
	ds_read_b128 v[158:161], v237 offset:32768
	ds_read_b128 v[162:165], v237 offset:33792
	ds_read_b128 v[166:169], v237 offset:34816
	ds_read_b128 v[178:181], v237 offset:35840
	ds_read_b128 v[182:185], v237 offset:36864
	ds_read_b128 v[186:189], v237 offset:37888
	ds_read_b128 v[190:193], v237 offset:38912
	ds_read_b128 v[214:217], v237 offset:39936
	global_load_lds_dwordx4 v[226:227], off
	v_lshl_add_u64 v[226:227], s[0:1], 0, v[204:205]
	s_mov_b32 m0, s43
	s_nop 0
	global_load_lds_dwordx4 v[226:227], off
	s_waitcnt vmcnt(8)
	s_waitcnt lgkmcnt(0)
	s_barrier
	s_setprio 1
	s_waitcnt lgkmcnt(0)
	v_mfma_f32_16x16x32_bf16 v[174:177], v[78:81], v[158:161], v[174:177]
	v_mfma_f32_16x16x32_bf16 v[174:177], v[90:93], v[162:165], v[174:177]
	v_mfma_f32_16x16x32_bf16 v[170:173], v[114:117], v[162:165], v[170:173]
	v_mfma_f32_16x16x32_bf16 v[170:173], v[102:105], v[158:161], v[170:173]
	v_mfma_f32_16x16x32_bf16 v[150:153], v[126:129], v[158:161], v[150:153]
	v_mfma_f32_16x16x32_bf16 v[150:153], v[134:137], v[162:165], v[150:153]
	v_mfma_f32_16x16x32_bf16 v[146:149], v[154:157], v[162:165], v[146:149]
	v_mfma_f32_16x16x32_bf16 v[146:149], v[142:145], v[158:161], v[146:149]
	v_mfma_f32_16x16x32_bf16 v[118:121], v[142:145], v[166:169], v[118:121]
	v_mfma_f32_16x16x32_bf16 v[118:121], v[154:157], v[178:181], v[118:121]
	v_mfma_f32_16x16x32_bf16 v[122:125], v[134:137], v[178:181], v[122:125]
	v_mfma_f32_16x16x32_bf16 v[122:125], v[126:129], v[166:169], v[122:125]
	v_mfma_f32_16x16x32_bf16 v[130:133], v[102:105], v[166:169], v[130:133]
	v_mfma_f32_16x16x32_bf16 v[130:133], v[114:117], v[178:181], v[130:133]
	v_mfma_f32_16x16x32_bf16 v[138:141], v[90:93], v[178:181], v[138:141]
	v_mfma_f32_16x16x32_bf16 v[138:141], v[78:81], v[166:169], v[138:141]
	v_mfma_f32_16x16x32_bf16 v[110:113], v[78:81], v[182:185], v[110:113]
	v_mfma_f32_16x16x32_bf16 v[110:113], v[90:93], v[186:189], v[110:113]
	v_mfma_f32_16x16x32_bf16 v[106:109], v[114:117], v[186:189], v[106:109]
	v_mfma_f32_16x16x32_bf16 v[106:109], v[102:105], v[182:185], v[106:109]
	v_mfma_f32_16x16x32_bf16 v[98:101], v[126:129], v[182:185], v[98:101]
	v_mfma_f32_16x16x32_bf16 v[98:101], v[134:137], v[186:189], v[98:101]
	v_mfma_f32_16x16x32_bf16 v[94:97], v[154:157], v[186:189], v[94:97]
	v_mfma_f32_16x16x32_bf16 v[94:97], v[142:145], v[182:185], v[94:97]
	v_mfma_f32_16x16x32_bf16 v[66:69], v[142:145], v[190:193], v[66:69]
	v_mfma_f32_16x16x32_bf16 v[66:69], v[154:157], v[214:217], v[66:69]
	v_mfma_f32_16x16x32_bf16 v[74:77], v[134:137], v[214:217], v[74:77]
	v_mfma_f32_16x16x32_bf16 v[74:77], v[126:129], v[190:193], v[74:77]
	v_mfma_f32_16x16x32_bf16 v[82:85], v[102:105], v[190:193], v[82:85]
	v_mfma_f32_16x16x32_bf16 v[82:85], v[114:117], v[214:217], v[82:85]
	v_mfma_f32_16x16x32_bf16 v[86:89], v[90:93], v[214:217], v[86:89]
	v_mfma_f32_16x16x32_bf16 v[86:89], v[78:81], v[190:193], v[86:89]
	s_setprio 0
	s_barrier
	s_add_i32 s0, s18, s28
	v_lshl_add_u64 v[218:219], v[218:219], 0, s[82:83]
	s_mov_b32 m0, s0
	ds_read_b128 v[158:161], v237 offset:49152
	ds_read_b128 v[162:165], v237 offset:50176
	ds_read_b128 v[166:169], v237 offset:51200
	ds_read_b128 v[178:181], v237 offset:52224
	ds_read_b128 v[182:185], v237 offset:53248
	ds_read_b128 v[186:189], v237 offset:54272
	ds_read_b128 v[190:193], v237 offset:55296
	ds_read_b128 v[214:217], v237 offset:56320
	global_load_lds_dwordx4 v[218:219], off
	s_add_i32 m0, s0, 0x2000
	s_add_u32 s0, s70, 0x80080
	v_lshl_add_u64 v[218:219], v[220:221], 0, s[82:83]
	s_addc_u32 s1, s71, 0
	s_add_i32 s18, s19, s28
	global_load_lds_dwordx4 v[218:219], off
	v_lshl_add_u64 v[218:219], s[0:1], 0, v[194:195]
	s_mov_b32 m0, s18
	s_nop 0
	global_load_lds_dwordx4 v[218:219], off
	v_lshl_add_u64 v[218:219], s[0:1], 0, v[204:205]
	s_add_i32 m0, s18, 0x2000
	s_nop 0
	global_load_lds_dwordx4 v[218:219], off
	v_lshl_add_u64 v[218:219], v[222:223], 0, s[82:83]
	s_mov_b32 m0, s68
	s_nop 0
	global_load_lds_dwordx4 v[218:219], off
	v_lshl_add_u64 v[218:219], v[224:225], 0, s[82:83]
	s_mov_b32 m0, s79
	s_nop 0
	global_load_lds_dwordx4 v[218:219], off
	s_waitcnt vmcnt(8)
	s_waitcnt lgkmcnt(0)
	s_barrier
	s_setprio 1
	s_waitcnt lgkmcnt(0)
	v_mfma_f32_16x16x32_bf16 v[62:65], v[78:81], v[158:161], v[62:65]
	v_mfma_f32_16x16x32_bf16 v[62:65], v[90:93], v[162:165], v[62:65]
	v_mfma_f32_16x16x32_bf16 v[58:61], v[114:117], v[162:165], v[58:61]
	v_mfma_f32_16x16x32_bf16 v[58:61], v[102:105], v[158:161], v[58:61]
	v_mfma_f32_16x16x32_bf16 v[54:57], v[126:129], v[158:161], v[54:57]
	v_mfma_f32_16x16x32_bf16 v[54:57], v[134:137], v[162:165], v[54:57]
	v_mfma_f32_16x16x32_bf16 v[50:53], v[154:157], v[162:165], v[50:53]
	v_mfma_f32_16x16x32_bf16 v[50:53], v[142:145], v[158:161], v[50:53]
	v_mfma_f32_16x16x32_bf16 v[34:37], v[142:145], v[166:169], v[34:37]
	v_mfma_f32_16x16x32_bf16 v[34:37], v[154:157], v[178:181], v[34:37]
	v_mfma_f32_16x16x32_bf16 v[38:41], v[134:137], v[178:181], v[38:41]
	v_mfma_f32_16x16x32_bf16 v[38:41], v[126:129], v[166:169], v[38:41]
	v_mfma_f32_16x16x32_bf16 v[42:45], v[102:105], v[166:169], v[42:45]
	v_mfma_f32_16x16x32_bf16 v[42:45], v[114:117], v[178:181], v[42:45]
	v_mfma_f32_16x16x32_bf16 v[46:49], v[90:93], v[178:181], v[46:49]
	v_mfma_f32_16x16x32_bf16 v[46:49], v[78:81], v[166:169], v[46:49]
	v_mfma_f32_16x16x32_bf16 v[30:33], v[78:81], v[182:185], v[30:33]
	v_mfma_f32_16x16x32_bf16 v[30:33], v[90:93], v[186:189], v[30:33]
	v_mfma_f32_16x16x32_bf16 v[26:29], v[114:117], v[186:189], v[26:29]
	v_mfma_f32_16x16x32_bf16 v[26:29], v[102:105], v[182:185], v[26:29]
	v_mfma_f32_16x16x32_bf16 v[22:25], v[126:129], v[182:185], v[22:25]
	v_mfma_f32_16x16x32_bf16 v[22:25], v[134:137], v[186:189], v[22:25]
	v_mfma_f32_16x16x32_bf16 v[18:21], v[154:157], v[186:189], v[18:21]
	v_mfma_f32_16x16x32_bf16 v[18:21], v[142:145], v[182:185], v[18:21]
	v_mfma_f32_16x16x32_bf16 v[2:5], v[142:145], v[190:193], v[2:5]
	v_mfma_f32_16x16x32_bf16 v[2:5], v[154:157], v[214:217], v[2:5]
	v_mfma_f32_16x16x32_bf16 v[6:9], v[134:137], v[214:217], v[6:9]
	v_mfma_f32_16x16x32_bf16 v[6:9], v[126:129], v[190:193], v[6:9]
	v_mfma_f32_16x16x32_bf16 v[10:13], v[102:105], v[190:193], v[10:13]
	v_mfma_f32_16x16x32_bf16 v[10:13], v[114:117], v[214:217], v[10:13]
	v_mfma_f32_16x16x32_bf16 v[14:17], v[90:93], v[214:217], v[14:17]
	v_mfma_f32_16x16x32_bf16 v[14:17], v[78:81], v[190:193], v[14:17]
	s_setprio 0
	s_barrier
	s_add_i32 s57, s57, 2
	s_add_u32 s51, s51, 0x100
	s_addc_u32 s53, s53, 0
	s_cmp_gt_u32 s57, 29
	s_mov_b64 s[76:77], s[90:91]
	s_cbranch_scc1 .LBB0_512

.LBB0_581:
	s_add_u32 s18, s62, 0xfff80080
	s_addc_u32 s19, s63, -1
	s_and_b64 s[0:1], s[64:65], exec
	s_cselect_b32 s71, s22, s19
	s_cselect_b32 s70, s23, s18
	s_cselect_b32 s65, s39, s58
	s_cselect_b32 s64, s47, s53
	s_add_i32 s0, 0, 0x10000
	v_add_u32_e32 v153, s0, v1
	s_add_i32 s18, 0, 0x14000
	ds_read_b128 v[144:147], v153
	ds_read_b128 v[148:151], v153 offset:1024
	ds_read_b128 v[154:157], v153 offset:2048
	ds_read_b128 v[158:161], v153 offset:3072
	v_add_u32_e32 v153, s18, v1
	ds_read_b128 v[162:165], v153
	ds_read_b128 v[166:169], v153 offset:1024
	ds_read_b128 v[170:173], v153 offset:2048
	ds_read_b128 v[174:177], v153 offset:3072
	v_lshl_add_u64 v[220:221], s[62:63], 0, v[136:137]
	s_add_i32 m0, s29, 0xc000
	ds_read_b128 v[178:181], v152
	ds_read_b128 v[182:185], v152 offset:1024
	ds_read_b128 v[186:189], v152 offset:2048
	ds_read_b128 v[190:193], v152 offset:3072
	ds_read_b128 v[204:207], v152 offset:4096
	ds_read_b128 v[208:211], v152 offset:5120
	ds_read_b128 v[212:215], v152 offset:6144
	ds_read_b128 v[216:219], v152 offset:7168
	global_load_lds_dwordx4 v[220:221], off
	v_lshl_add_u64 v[220:221], s[62:63], 0, v[138:139]
	s_add_i32 m0, s29, 0xe000
	s_nop 0
	global_load_lds_dwordx4 v[220:221], off
	s_waitcnt vmcnt(8)
	s_waitcnt lgkmcnt(0)
	s_barrier
	s_setprio 1
	s_waitcnt lgkmcnt(0)
	v_mfma_f32_16x16x32_bf16 v[126:129], v[144:147], v[178:181], v[126:129]
	v_mfma_f32_16x16x32_bf16 v[126:129], v[148:151], v[182:185], v[126:129]
	v_mfma_f32_16x16x32_bf16 v[122:125], v[158:161], v[182:185], v[122:125]
	v_mfma_f32_16x16x32_bf16 v[122:125], v[154:157], v[178:181], v[122:125]
	v_mfma_f32_16x16x32_bf16 v[118:121], v[162:165], v[178:181], v[118:121]
	v_mfma_f32_16x16x32_bf16 v[118:121], v[166:169], v[182:185], v[118:121]
	v_mfma_f32_16x16x32_bf16 v[114:117], v[174:177], v[182:185], v[114:117]
	v_mfma_f32_16x16x32_bf16 v[114:117], v[170:173], v[178:181], v[114:117]
	v_mfma_f32_16x16x32_bf16 v[98:101], v[170:173], v[186:189], v[98:101]
	v_mfma_f32_16x16x32_bf16 v[98:101], v[174:177], v[190:193], v[98:101]
	v_mfma_f32_16x16x32_bf16 v[102:105], v[166:169], v[190:193], v[102:105]
	v_mfma_f32_16x16x32_bf16 v[102:105], v[162:165], v[186:189], v[102:105]
	v_mfma_f32_16x16x32_bf16 v[106:109], v[154:157], v[186:189], v[106:109]
	v_mfma_f32_16x16x32_bf16 v[106:109], v[158:161], v[190:193], v[106:109]
	v_mfma_f32_16x16x32_bf16 v[110:113], v[148:151], v[190:193], v[110:113]
	v_mfma_f32_16x16x32_bf16 v[110:113], v[144:147], v[186:189], v[110:113]
	v_mfma_f32_16x16x32_bf16 v[94:97], v[144:147], v[204:207], v[94:97]
	v_mfma_f32_16x16x32_bf16 v[94:97], v[148:151], v[208:211], v[94:97]
	v_mfma_f32_16x16x32_bf16 v[90:93], v[158:161], v[208:211], v[90:93]
	v_mfma_f32_16x16x32_bf16 v[90:93], v[154:157], v[204:207], v[90:93]
	v_mfma_f32_16x16x32_bf16 v[86:89], v[162:165], v[204:207], v[86:89]
	v_mfma_f32_16x16x32_bf16 v[86:89], v[166:169], v[208:211], v[86:89]
	v_mfma_f32_16x16x32_bf16 v[82:85], v[174:177], v[208:211], v[82:85]
	v_mfma_f32_16x16x32_bf16 v[82:85], v[170:173], v[204:207], v[82:85]
	v_mfma_f32_16x16x32_bf16 v[66:69], v[170:173], v[212:215], v[66:69]
	v_mfma_f32_16x16x32_bf16 v[66:69], v[174:177], v[216:219], v[66:69]
	v_mfma_f32_16x16x32_bf16 v[70:73], v[166:169], v[216:219], v[70:73]
	v_mfma_f32_16x16x32_bf16 v[70:73], v[162:165], v[212:215], v[70:73]
	v_mfma_f32_16x16x32_bf16 v[74:77], v[154:157], v[212:215], v[74:77]
	v_mfma_f32_16x16x32_bf16 v[74:77], v[158:161], v[216:219], v[74:77]
	v_mfma_f32_16x16x32_bf16 v[78:81], v[148:151], v[216:219], v[78:81]
	v_mfma_f32_16x16x32_bf16 v[78:81], v[144:147], v[212:215], v[78:81]
	s_setprio 0
	s_barrier
	s_add_i32 s0, s0, s28
	v_lshl_add_u64 v[220:221], s[64:65], 0, v[194:195]
	s_mov_b32 m0, s0
	ds_read_b128 v[178:181], v152 offset:16384
	ds_read_b128 v[182:185], v152 offset:17408
	ds_read_b128 v[186:189], v152 offset:18432
	ds_read_b128 v[190:193], v152 offset:19456
	ds_read_b128 v[204:207], v152 offset:20480
	ds_read_b128 v[208:211], v152 offset:21504
	ds_read_b128 v[212:215], v152 offset:22528
	ds_read_b128 v[216:219], v152 offset:23552
	global_load_lds_dwordx4 v[220:221], off
	s_add_i32 m0, s0, 0x2000
	s_add_u32 s0, s64, 0x80000
	v_lshl_add_u64 v[222:223], s[64:65], 0, v[130:131]
	s_addc_u32 s1, s65, 0
	s_add_i32 s18, s18, s28
	global_load_lds_dwordx4 v[222:223], off
	v_lshl_add_u64 v[224:225], s[0:1], 0, v[194:195]
	s_mov_b32 m0, s18
	v_lshl_add_u64 v[226:227], s[70:71], 0, v[130:131]
	global_load_lds_dwordx4 v[224:225], off
	v_lshl_add_u64 v[224:225], s[0:1], 0, v[130:131]
	s_add_i32 m0, s18, 0x2000
	s_nop 0
	global_load_lds_dwordx4 v[224:225], off
	v_lshl_add_u64 v[224:225], s[70:71], 0, v[194:195]
	s_mov_b32 m0, s29
	s_nop 0
	global_load_lds_dwordx4 v[224:225], off
	s_mov_b32 m0, s31
	s_nop 0
	global_load_lds_dwordx4 v[226:227], off
	s_waitcnt vmcnt(8)
	s_waitcnt lgkmcnt(0)
	s_barrier
	s_setprio 1
	s_waitcnt lgkmcnt(0)
	v_mfma_f32_16x16x32_bf16 v[62:65], v[144:147], v[178:181], v[62:65]
	v_mfma_f32_16x16x32_bf16 v[62:65], v[148:151], v[182:185], v[62:65]
	v_mfma_f32_16x16x32_bf16 v[58:61], v[158:161], v[182:185], v[58:61]
	v_mfma_f32_16x16x32_bf16 v[58:61], v[154:157], v[178:181], v[58:61]
	v_mfma_f32_16x16x32_bf16 v[54:57], v[162:165], v[178:181], v[54:57]
	v_mfma_f32_16x16x32_bf16 v[54:57], v[166:169], v[182:185], v[54:57]
	v_mfma_f32_16x16x32_bf16 v[50:53], v[174:177], v[182:185], v[50:53]
	v_mfma_f32_16x16x32_bf16 v[50:53], v[170:173], v[178:181], v[50:53]
	v_mfma_f32_16x16x32_bf16 v[34:37], v[170:173], v[186:189], v[34:37]
	v_mfma_f32_16x16x32_bf16 v[34:37], v[174:177], v[190:193], v[34:37]
	v_mfma_f32_16x16x32_bf16 v[38:41], v[166:169], v[190:193], v[38:41]
	v_mfma_f32_16x16x32_bf16 v[38:41], v[162:165], v[186:189], v[38:41]
	v_mfma_f32_16x16x32_bf16 v[42:45], v[154:157], v[186:189], v[42:45]
	v_mfma_f32_16x16x32_bf16 v[42:45], v[158:161], v[190:193], v[42:45]
	v_mfma_f32_16x16x32_bf16 v[46:49], v[148:151], v[190:193], v[46:49]
	v_mfma_f32_16x16x32_bf16 v[46:49], v[144:147], v[186:189], v[46:49]
	v_mfma_f32_16x16x32_bf16 v[30:33], v[144:147], v[204:207], v[30:33]
	v_mfma_f32_16x16x32_bf16 v[30:33], v[148:151], v[208:211], v[30:33]
	v_mfma_f32_16x16x32_bf16 v[26:29], v[158:161], v[208:211], v[26:29]
	v_mfma_f32_16x16x32_bf16 v[26:29], v[154:157], v[204:207], v[26:29]
	v_mfma_f32_16x16x32_bf16 v[22:25], v[162:165], v[204:207], v[22:25]
	v_mfma_f32_16x16x32_bf16 v[22:25], v[166:169], v[208:211], v[22:25]
	v_mfma_f32_16x16x32_bf16 v[18:21], v[174:177], v[208:211], v[18:21]
	v_mfma_f32_16x16x32_bf16 v[18:21], v[170:173], v[204:207], v[18:21]
	v_mfma_f32_16x16x32_bf16 v[2:5], v[170:173], v[212:215], v[2:5]
	v_mfma_f32_16x16x32_bf16 v[2:5], v[174:177], v[216:219], v[2:5]
	v_mfma_f32_16x16x32_bf16 v[6:9], v[166:169], v[216:219], v[6:9]
	v_mfma_f32_16x16x32_bf16 v[6:9], v[162:165], v[212:215], v[6:9]
	v_mfma_f32_16x16x32_bf16 v[10:13], v[154:157], v[212:215], v[10:13]
	v_mfma_f32_16x16x32_bf16 v[10:13], v[158:161], v[216:219], v[10:13]
	v_mfma_f32_16x16x32_bf16 v[14:17], v[148:151], v[216:219], v[14:17]
	v_mfma_f32_16x16x32_bf16 v[14:17], v[144:147], v[212:215], v[14:17]
	s_setprio 0
	s_barrier
	s_add_i32 s18, 0, 0x18000
	v_add_u32_e32 v153, s18, v1
	s_add_i32 s19, 0, 0x1c000
	ds_read_b128 v[144:147], v153
	ds_read_b128 v[148:151], v153 offset:1024
	ds_read_b128 v[154:157], v153 offset:2048
	ds_read_b128 v[158:161], v153 offset:3072
	v_add_u32_e32 v153, s19, v1
	ds_read_b128 v[162:165], v153
	ds_read_b128 v[166:169], v153 offset:1024
	ds_read_b128 v[170:173], v153 offset:2048
	ds_read_b128 v[174:177], v153 offset:3072
	s_add_u32 s0, s70, 0x80000
	s_addc_u32 s1, s71, 0
	s_mov_b32 m0, s33
	v_lshl_add_u64 v[228:229], s[0:1], 0, v[194:195]
	ds_read_b128 v[178:181], v152 offset:32768
	ds_read_b128 v[182:185], v152 offset:33792
	ds_read_b128 v[186:189], v152 offset:34816
	ds_read_b128 v[190:193], v152 offset:35840
	ds_read_b128 v[204:207], v152 offset:36864
	ds_read_b128 v[208:211], v152 offset:37888
	ds_read_b128 v[212:215], v152 offset:38912
	ds_read_b128 v[216:219], v152 offset:39936
	global_load_lds_dwordx4 v[228:229], off
	v_lshl_add_u64 v[228:229], s[0:1], 0, v[130:131]
	s_mov_b32 m0, s40
	s_nop 0
	global_load_lds_dwordx4 v[228:229], off
	s_waitcnt vmcnt(8)
	s_waitcnt lgkmcnt(0)
	s_barrier
	s_setprio 1
	s_waitcnt lgkmcnt(0)
	v_mfma_f32_16x16x32_bf16 v[126:129], v[144:147], v[178:181], v[126:129]
	v_mfma_f32_16x16x32_bf16 v[126:129], v[148:151], v[182:185], v[126:129]
	v_mfma_f32_16x16x32_bf16 v[122:125], v[158:161], v[182:185], v[122:125]
	v_mfma_f32_16x16x32_bf16 v[122:125], v[154:157], v[178:181], v[122:125]
	v_mfma_f32_16x16x32_bf16 v[118:121], v[162:165], v[178:181], v[118:121]
	v_mfma_f32_16x16x32_bf16 v[118:121], v[166:169], v[182:185], v[118:121]
	v_mfma_f32_16x16x32_bf16 v[114:117], v[174:177], v[182:185], v[114:117]
	v_mfma_f32_16x16x32_bf16 v[114:117], v[170:173], v[178:181], v[114:117]
	v_mfma_f32_16x16x32_bf16 v[98:101], v[170:173], v[186:189], v[98:101]
	v_mfma_f32_16x16x32_bf16 v[98:101], v[174:177], v[190:193], v[98:101]
	v_mfma_f32_16x16x32_bf16 v[102:105], v[166:169], v[190:193], v[102:105]
	v_mfma_f32_16x16x32_bf16 v[102:105], v[162:165], v[186:189], v[102:105]
	v_mfma_f32_16x16x32_bf16 v[106:109], v[154:157], v[186:189], v[106:109]
	v_mfma_f32_16x16x32_bf16 v[106:109], v[158:161], v[190:193], v[106:109]
	v_mfma_f32_16x16x32_bf16 v[110:113], v[148:151], v[190:193], v[110:113]
	v_mfma_f32_16x16x32_bf16 v[110:113], v[144:147], v[186:189], v[110:113]
	v_mfma_f32_16x16x32_bf16 v[94:97], v[144:147], v[204:207], v[94:97]
	v_mfma_f32_16x16x32_bf16 v[94:97], v[148:151], v[208:211], v[94:97]
	v_mfma_f32_16x16x32_bf16 v[90:93], v[158:161], v[208:211], v[90:93]
	v_mfma_f32_16x16x32_bf16 v[90:93], v[154:157], v[204:207], v[90:93]
	v_mfma_f32_16x16x32_bf16 v[86:89], v[162:165], v[204:207], v[86:89]
	v_mfma_f32_16x16x32_bf16 v[86:89], v[166:169], v[208:211], v[86:89]
	v_mfma_f32_16x16x32_bf16 v[82:85], v[174:177], v[208:211], v[82:85]
	v_mfma_f32_16x16x32_bf16 v[82:85], v[170:173], v[204:207], v[82:85]
	v_mfma_f32_16x16x32_bf16 v[66:69], v[170:173], v[212:215], v[66:69]
	v_mfma_f32_16x16x32_bf16 v[66:69], v[174:177], v[216:219], v[66:69]
	v_mfma_f32_16x16x32_bf16 v[70:73], v[166:169], v[216:219], v[70:73]
	v_mfma_f32_16x16x32_bf16 v[70:73], v[162:165], v[212:215], v[70:73]
	v_mfma_f32_16x16x32_bf16 v[74:77], v[154:157], v[212:215], v[74:77]
	v_mfma_f32_16x16x32_bf16 v[74:77], v[158:161], v[216:219], v[74:77]
	v_mfma_f32_16x16x32_bf16 v[78:81], v[148:151], v[216:219], v[78:81]
	v_mfma_f32_16x16x32_bf16 v[78:81], v[144:147], v[212:215], v[78:81]
	s_setprio 0
	s_barrier
	s_add_i32 s0, s18, s28
	v_lshl_add_u64 v[220:221], v[220:221], 0, s[82:83]
	s_mov_b32 m0, s0
	ds_read_b128 v[178:181], v152 offset:49152
	ds_read_b128 v[182:185], v152 offset:50176
	ds_read_b128 v[186:189], v152 offset:51200
	ds_read_b128 v[190:193], v152 offset:52224
	ds_read_b128 v[204:207], v152 offset:53248
	ds_read_b128 v[208:211], v152 offset:54272
	ds_read_b128 v[212:215], v152 offset:55296
	ds_read_b128 v[216:219], v152 offset:56320
	global_load_lds_dwordx4 v[220:221], off
	s_add_i32 m0, s0, 0x2000
	s_add_u32 s0, s64, 0x80080
	v_lshl_add_u64 v[220:221], v[222:223], 0, s[82:83]
	s_addc_u32 s1, s65, 0
	s_add_i32 s18, s19, s28
	global_load_lds_dwordx4 v[220:221], off
	v_lshl_add_u64 v[220:221], s[0:1], 0, v[194:195]
	s_mov_b32 m0, s18
	s_nop 0
	global_load_lds_dwordx4 v[220:221], off
	v_lshl_add_u64 v[220:221], s[0:1], 0, v[130:131]
	s_add_i32 m0, s18, 0x2000
	s_nop 0
	global_load_lds_dwordx4 v[220:221], off
	v_lshl_add_u64 v[220:221], v[224:225], 0, s[82:83]
	s_mov_b32 m0, s54
	s_nop 0
	global_load_lds_dwordx4 v[220:221], off
	v_lshl_add_u64 v[220:221], v[226:227], 0, s[82:83]
	s_mov_b32 m0, s57
	s_nop 0
	global_load_lds_dwordx4 v[220:221], off
	s_waitcnt vmcnt(8)
	s_waitcnt lgkmcnt(0)
	s_barrier
	s_setprio 1
	s_waitcnt lgkmcnt(0)
	v_mfma_f32_16x16x32_bf16 v[62:65], v[144:147], v[178:181], v[62:65]
	v_mfma_f32_16x16x32_bf16 v[62:65], v[148:151], v[182:185], v[62:65]
	v_mfma_f32_16x16x32_bf16 v[58:61], v[158:161], v[182:185], v[58:61]
	v_mfma_f32_16x16x32_bf16 v[58:61], v[154:157], v[178:181], v[58:61]
	v_mfma_f32_16x16x32_bf16 v[54:57], v[162:165], v[178:181], v[54:57]
	v_mfma_f32_16x16x32_bf16 v[54:57], v[166:169], v[182:185], v[54:57]
	v_mfma_f32_16x16x32_bf16 v[50:53], v[174:177], v[182:185], v[50:53]
	v_mfma_f32_16x16x32_bf16 v[50:53], v[170:173], v[178:181], v[50:53]
	v_mfma_f32_16x16x32_bf16 v[34:37], v[170:173], v[186:189], v[34:37]
	v_mfma_f32_16x16x32_bf16 v[34:37], v[174:177], v[190:193], v[34:37]
	v_mfma_f32_16x16x32_bf16 v[38:41], v[166:169], v[190:193], v[38:41]
	v_mfma_f32_16x16x32_bf16 v[38:41], v[162:165], v[186:189], v[38:41]
	v_mfma_f32_16x16x32_bf16 v[42:45], v[154:157], v[186:189], v[42:45]
	v_mfma_f32_16x16x32_bf16 v[42:45], v[158:161], v[190:193], v[42:45]
	v_mfma_f32_16x16x32_bf16 v[46:49], v[148:151], v[190:193], v[46:49]
	v_mfma_f32_16x16x32_bf16 v[46:49], v[144:147], v[186:189], v[46:49]
	v_mfma_f32_16x16x32_bf16 v[30:33], v[144:147], v[204:207], v[30:33]
	v_mfma_f32_16x16x32_bf16 v[30:33], v[148:151], v[208:211], v[30:33]
	v_mfma_f32_16x16x32_bf16 v[26:29], v[158:161], v[208:211], v[26:29]
	v_mfma_f32_16x16x32_bf16 v[26:29], v[154:157], v[204:207], v[26:29]
	v_mfma_f32_16x16x32_bf16 v[22:25], v[162:165], v[204:207], v[22:25]
	v_mfma_f32_16x16x32_bf16 v[22:25], v[166:169], v[208:211], v[22:25]
	v_mfma_f32_16x16x32_bf16 v[18:21], v[174:177], v[208:211], v[18:21]
	v_mfma_f32_16x16x32_bf16 v[18:21], v[170:173], v[204:207], v[18:21]
	v_mfma_f32_16x16x32_bf16 v[2:5], v[170:173], v[212:215], v[2:5]
	v_mfma_f32_16x16x32_bf16 v[2:5], v[174:177], v[216:219], v[2:5]
	v_mfma_f32_16x16x32_bf16 v[6:9], v[166:169], v[216:219], v[6:9]
	v_mfma_f32_16x16x32_bf16 v[6:9], v[162:165], v[212:215], v[6:9]
	v_mfma_f32_16x16x32_bf16 v[10:13], v[154:157], v[212:215], v[10:13]
	v_mfma_f32_16x16x32_bf16 v[10:13], v[158:161], v[216:219], v[10:13]
	v_mfma_f32_16x16x32_bf16 v[14:17], v[148:151], v[216:219], v[14:17]
	v_mfma_f32_16x16x32_bf16 v[14:17], v[144:147], v[212:215], v[14:17]
	s_setprio 0
	s_barrier
	s_add_i32 s76, s76, 2
	s_add_u32 s62, s62, 0x100
	s_addc_u32 s63, s63, 0
	s_add_u32 s53, s53, 0x100
	s_addc_u32 s58, s58, 0
	s_cmp_gt_u32 s76, 29
	s_cbranch_scc1 .LBB0_584

.LBB0_645:
	s_add_u32 s64, s8, 0x100
	s_addc_u32 s65, s9, 0
	s_and_b64 s[0:1], s[70:71], exec
	s_cselect_b32 s77, s63, s65
	s_cselect_b32 s76, s62, s64
	s_cselect_b32 s71, s85, s23
	s_cselect_b32 s70, s84, s7
	s_add_i32 s0, 0, 0x10000
	s_add_i32 s18, 0, 0x14000
	v_add_u32_e32 v106, s0, v1
	v_add_u32_e32 v154, s18, v1
	ds_read_b128 v[70:73], v106
	ds_read_b128 v[82:85], v106 offset:1024
	ds_read_b128 v[94:97], v106 offset:2048
	ds_read_b128 v[106:109], v106 offset:3072
	ds_read_b128 v[118:121], v154
	ds_read_b128 v[130:133], v154 offset:1024
	ds_read_b128 v[142:145], v154 offset:2048
	ds_read_b128 v[154:157], v154 offset:3072
	v_lshl_add_u64 v[218:219], s[8:9], 0, v[206:207]
	s_add_i32 m0, s29, 0xc000
	ds_read_b128 v[158:161], v237
	ds_read_b128 v[170:173], v237 offset:1024
	ds_read_b128 v[174:177], v237 offset:2048
	ds_read_b128 v[178:181], v237 offset:3072
	ds_read_b128 v[182:185], v237 offset:4096
	ds_read_b128 v[186:189], v237 offset:5120
	ds_read_b128 v[210:213], v237 offset:6144
	ds_read_b128 v[214:217], v237 offset:7168
	global_load_lds_dwordx4 v[218:219], off
	v_lshl_add_u64 v[218:219], s[8:9], 0, v[208:209]
	s_add_i32 m0, s29, 0xe000
	s_nop 0
	global_load_lds_dwordx4 v[218:219], off
	s_waitcnt vmcnt(8)
	s_waitcnt lgkmcnt(0)
	s_barrier
	s_setprio 1
	s_waitcnt lgkmcnt(0)
	v_mfma_f32_16x16x32_bf16 v[166:169], v[70:73], v[158:161], v[166:169]
	v_mfma_f32_16x16x32_bf16 v[166:169], v[82:85], v[170:173], v[166:169]
	v_mfma_f32_16x16x32_bf16 v[162:165], v[106:109], v[170:173], v[162:165]
	v_mfma_f32_16x16x32_bf16 v[162:165], v[94:97], v[158:161], v[162:165]
	v_mfma_f32_16x16x32_bf16 v[150:153], v[118:121], v[158:161], v[150:153]
	v_mfma_f32_16x16x32_bf16 v[150:153], v[130:133], v[170:173], v[150:153]
	v_mfma_f32_16x16x32_bf16 v[146:149], v[154:157], v[170:173], v[146:149]
	v_mfma_f32_16x16x32_bf16 v[146:149], v[142:145], v[158:161], v[146:149]
	v_mfma_f32_16x16x32_bf16 v[122:125], v[142:145], v[174:177], v[122:125]
	v_mfma_f32_16x16x32_bf16 v[122:125], v[154:157], v[178:181], v[122:125]
	v_mfma_f32_16x16x32_bf16 v[126:129], v[130:133], v[178:181], v[126:129]
	v_mfma_f32_16x16x32_bf16 v[126:129], v[118:121], v[174:177], v[126:129]
	v_mfma_f32_16x16x32_bf16 v[134:137], v[94:97], v[174:177], v[134:137]
	v_mfma_f32_16x16x32_bf16 v[134:137], v[106:109], v[178:181], v[134:137]
	v_mfma_f32_16x16x32_bf16 v[138:141], v[82:85], v[178:181], v[138:141]
	v_mfma_f32_16x16x32_bf16 v[138:141], v[70:73], v[174:177], v[138:141]
	v_mfma_f32_16x16x32_bf16 v[114:117], v[70:73], v[182:185], v[114:117]
	v_mfma_f32_16x16x32_bf16 v[114:117], v[82:85], v[186:189], v[114:117]
	v_mfma_f32_16x16x32_bf16 v[110:113], v[106:109], v[186:189], v[110:113]
	v_mfma_f32_16x16x32_bf16 v[110:113], v[94:97], v[182:185], v[110:113]
	v_mfma_f32_16x16x32_bf16 v[102:105], v[118:121], v[182:185], v[102:105]
	v_mfma_f32_16x16x32_bf16 v[102:105], v[130:133], v[186:189], v[102:105]
	v_mfma_f32_16x16x32_bf16 v[98:101], v[154:157], v[186:189], v[98:101]
	v_mfma_f32_16x16x32_bf16 v[98:101], v[142:145], v[182:185], v[98:101]
	v_mfma_f32_16x16x32_bf16 v[74:77], v[142:145], v[210:213], v[74:77]
	v_mfma_f32_16x16x32_bf16 v[74:77], v[154:157], v[214:217], v[74:77]
	v_mfma_f32_16x16x32_bf16 v[78:81], v[130:133], v[214:217], v[78:81]
	v_mfma_f32_16x16x32_bf16 v[78:81], v[118:121], v[210:213], v[78:81]
	v_mfma_f32_16x16x32_bf16 v[86:89], v[94:97], v[210:213], v[86:89]
	v_mfma_f32_16x16x32_bf16 v[86:89], v[106:109], v[214:217], v[86:89]
	v_mfma_f32_16x16x32_bf16 v[90:93], v[82:85], v[214:217], v[90:93]
	v_mfma_f32_16x16x32_bf16 v[90:93], v[70:73], v[210:213], v[90:93]
	s_setprio 0
	s_barrier
	s_add_i32 s0, s0, s28
	v_lshl_add_u64 v[218:219], s[70:71], 0, v[192:193]
	s_mov_b32 m0, s0
	ds_read_b128 v[158:161], v237 offset:16384
	ds_read_b128 v[170:173], v237 offset:17408
	ds_read_b128 v[174:177], v237 offset:18432
	ds_read_b128 v[178:181], v237 offset:19456
	ds_read_b128 v[182:185], v237 offset:20480
	ds_read_b128 v[186:189], v237 offset:21504
	ds_read_b128 v[210:213], v237 offset:22528
	ds_read_b128 v[214:217], v237 offset:23552
	global_load_lds_dwordx4 v[218:219], off
	s_add_i32 m0, s0, 0x2000
	s_add_u32 s0, s70, 0x160000
	v_lshl_add_u64 v[220:221], s[70:71], 0, v[190:191]
	s_addc_u32 s1, s71, 0
	s_add_i32 s8, s18, s28
	global_load_lds_dwordx4 v[220:221], off
	v_lshl_add_u64 v[222:223], s[0:1], 0, v[192:193]
	s_mov_b32 m0, s8
	v_lshl_add_u64 v[224:225], s[76:77], 0, v[190:191]
	global_load_lds_dwordx4 v[222:223], off
	v_lshl_add_u64 v[222:223], s[0:1], 0, v[190:191]
	s_add_i32 m0, s8, 0x2000
	s_nop 0
	global_load_lds_dwordx4 v[222:223], off
	v_lshl_add_u64 v[222:223], s[76:77], 0, v[192:193]
	s_mov_b32 m0, s29
	s_nop 0
	global_load_lds_dwordx4 v[222:223], off
	s_mov_b32 m0, s31
	s_nop 0
	global_load_lds_dwordx4 v[224:225], off
	s_waitcnt vmcnt(8)
	s_waitcnt lgkmcnt(0)
	s_barrier
	s_setprio 1
	s_waitcnt lgkmcnt(0)
	v_mfma_f32_16x16x32_bf16 v[62:65], v[70:73], v[158:161], v[62:65]
	v_mfma_f32_16x16x32_bf16 v[62:65], v[82:85], v[170:173], v[62:65]
	v_mfma_f32_16x16x32_bf16 v[58:61], v[106:109], v[170:173], v[58:61]
	v_mfma_f32_16x16x32_bf16 v[58:61], v[94:97], v[158:161], v[58:61]
	v_mfma_f32_16x16x32_bf16 v[54:57], v[118:121], v[158:161], v[54:57]
	v_mfma_f32_16x16x32_bf16 v[54:57], v[130:133], v[170:173], v[54:57]
	v_mfma_f32_16x16x32_bf16 v[50:53], v[154:157], v[170:173], v[50:53]
	v_mfma_f32_16x16x32_bf16 v[50:53], v[142:145], v[158:161], v[50:53]
	v_mfma_f32_16x16x32_bf16 v[34:37], v[142:145], v[174:177], v[34:37]
	v_mfma_f32_16x16x32_bf16 v[34:37], v[154:157], v[178:181], v[34:37]
	v_mfma_f32_16x16x32_bf16 v[38:41], v[130:133], v[178:181], v[38:41]
	v_mfma_f32_16x16x32_bf16 v[38:41], v[118:121], v[174:177], v[38:41]
	v_mfma_f32_16x16x32_bf16 v[42:45], v[94:97], v[174:177], v[42:45]
	v_mfma_f32_16x16x32_bf16 v[42:45], v[106:109], v[178:181], v[42:45]
	v_mfma_f32_16x16x32_bf16 v[46:49], v[82:85], v[178:181], v[46:49]
	v_mfma_f32_16x16x32_bf16 v[46:49], v[70:73], v[174:177], v[46:49]
	v_mfma_f32_16x16x32_bf16 v[30:33], v[70:73], v[182:185], v[30:33]
	v_mfma_f32_16x16x32_bf16 v[30:33], v[82:85], v[186:189], v[30:33]
	v_mfma_f32_16x16x32_bf16 v[26:29], v[106:109], v[186:189], v[26:29]
	v_mfma_f32_16x16x32_bf16 v[26:29], v[94:97], v[182:185], v[26:29]
	v_mfma_f32_16x16x32_bf16 v[22:25], v[118:121], v[182:185], v[22:25]
	v_mfma_f32_16x16x32_bf16 v[22:25], v[130:133], v[186:189], v[22:25]
	v_mfma_f32_16x16x32_bf16 v[18:21], v[154:157], v[186:189], v[18:21]
	v_mfma_f32_16x16x32_bf16 v[18:21], v[142:145], v[182:185], v[18:21]
	v_mfma_f32_16x16x32_bf16 v[2:5], v[142:145], v[210:213], v[2:5]
	v_mfma_f32_16x16x32_bf16 v[2:5], v[154:157], v[214:217], v[2:5]
	v_mfma_f32_16x16x32_bf16 v[6:9], v[130:133], v[214:217], v[6:9]
	v_mfma_f32_16x16x32_bf16 v[6:9], v[118:121], v[210:213], v[6:9]
	v_mfma_f32_16x16x32_bf16 v[10:13], v[94:97], v[210:213], v[10:13]
	v_mfma_f32_16x16x32_bf16 v[10:13], v[106:109], v[214:217], v[10:13]
	v_mfma_f32_16x16x32_bf16 v[14:17], v[82:85], v[214:217], v[14:17]
	v_mfma_f32_16x16x32_bf16 v[14:17], v[70:73], v[210:213], v[14:17]
	s_setprio 0
	s_barrier
	s_add_i32 s8, 0, 0x18000
	s_add_i32 s9, 0, 0x1c000
	v_add_u32_e32 v106, s8, v1
	v_add_u32_e32 v154, s9, v1
	ds_read_b128 v[70:73], v106
	ds_read_b128 v[82:85], v106 offset:1024
	ds_read_b128 v[94:97], v106 offset:2048
	ds_read_b128 v[106:109], v106 offset:3072
	ds_read_b128 v[118:121], v154
	ds_read_b128 v[130:133], v154 offset:1024
	ds_read_b128 v[142:145], v154 offset:2048
	ds_read_b128 v[154:157], v154 offset:3072
	s_add_u32 s0, s76, 0x160000
	s_addc_u32 s1, s77, 0
	s_mov_b32 m0, s33
	v_lshl_add_u64 v[226:227], s[0:1], 0, v[192:193]
	ds_read_b128 v[158:161], v237 offset:32768
	ds_read_b128 v[170:173], v237 offset:33792
	ds_read_b128 v[174:177], v237 offset:34816
	ds_read_b128 v[178:181], v237 offset:35840
	ds_read_b128 v[182:185], v237 offset:36864
	ds_read_b128 v[186:189], v237 offset:37888
	ds_read_b128 v[210:213], v237 offset:38912
	ds_read_b128 v[214:217], v237 offset:39936
	global_load_lds_dwordx4 v[226:227], off
	v_lshl_add_u64 v[226:227], s[0:1], 0, v[190:191]
	s_mov_b32 m0, s43
	s_nop 0
	global_load_lds_dwordx4 v[226:227], off
	s_waitcnt vmcnt(8)
	s_waitcnt lgkmcnt(0)
	s_barrier
	s_setprio 1
	s_waitcnt lgkmcnt(0)
	v_mfma_f32_16x16x32_bf16 v[166:169], v[70:73], v[158:161], v[166:169]
	v_mfma_f32_16x16x32_bf16 v[166:169], v[82:85], v[170:173], v[166:169]
	v_mfma_f32_16x16x32_bf16 v[162:165], v[106:109], v[170:173], v[162:165]
	v_mfma_f32_16x16x32_bf16 v[162:165], v[94:97], v[158:161], v[162:165]
	v_mfma_f32_16x16x32_bf16 v[150:153], v[118:121], v[158:161], v[150:153]
	v_mfma_f32_16x16x32_bf16 v[150:153], v[130:133], v[170:173], v[150:153]
	v_mfma_f32_16x16x32_bf16 v[146:149], v[154:157], v[170:173], v[146:149]
	v_mfma_f32_16x16x32_bf16 v[146:149], v[142:145], v[158:161], v[146:149]
	v_mfma_f32_16x16x32_bf16 v[122:125], v[142:145], v[174:177], v[122:125]
	v_mfma_f32_16x16x32_bf16 v[122:125], v[154:157], v[178:181], v[122:125]
	v_mfma_f32_16x16x32_bf16 v[126:129], v[130:133], v[178:181], v[126:129]
	v_mfma_f32_16x16x32_bf16 v[126:129], v[118:121], v[174:177], v[126:129]
	v_mfma_f32_16x16x32_bf16 v[134:137], v[94:97], v[174:177], v[134:137]
	v_mfma_f32_16x16x32_bf16 v[134:137], v[106:109], v[178:181], v[134:137]
	v_mfma_f32_16x16x32_bf16 v[138:141], v[82:85], v[178:181], v[138:141]
	v_mfma_f32_16x16x32_bf16 v[138:141], v[70:73], v[174:177], v[138:141]
	v_mfma_f32_16x16x32_bf16 v[114:117], v[70:73], v[182:185], v[114:117]
	v_mfma_f32_16x16x32_bf16 v[114:117], v[82:85], v[186:189], v[114:117]
	v_mfma_f32_16x16x32_bf16 v[110:113], v[106:109], v[186:189], v[110:113]
	v_mfma_f32_16x16x32_bf16 v[110:113], v[94:97], v[182:185], v[110:113]
	v_mfma_f32_16x16x32_bf16 v[102:105], v[118:121], v[182:185], v[102:105]
	v_mfma_f32_16x16x32_bf16 v[102:105], v[130:133], v[186:189], v[102:105]
	v_mfma_f32_16x16x32_bf16 v[98:101], v[154:157], v[186:189], v[98:101]
	v_mfma_f32_16x16x32_bf16 v[98:101], v[142:145], v[182:185], v[98:101]
	v_mfma_f32_16x16x32_bf16 v[74:77], v[142:145], v[210:213], v[74:77]
	v_mfma_f32_16x16x32_bf16 v[74:77], v[154:157], v[214:217], v[74:77]
	v_mfma_f32_16x16x32_bf16 v[78:81], v[130:133], v[214:217], v[78:81]
	v_mfma_f32_16x16x32_bf16 v[78:81], v[118:121], v[210:213], v[78:81]
	v_mfma_f32_16x16x32_bf16 v[86:89], v[94:97], v[210:213], v[86:89]
	v_mfma_f32_16x16x32_bf16 v[86:89], v[106:109], v[214:217], v[86:89]
	v_mfma_f32_16x16x32_bf16 v[90:93], v[82:85], v[214:217], v[90:93]
	v_mfma_f32_16x16x32_bf16 v[90:93], v[70:73], v[210:213], v[90:93]
	s_setprio 0
	s_barrier
	s_add_i32 s0, s8, s28
	v_lshl_add_u64 v[218:219], v[218:219], 0, s[82:83]
	s_mov_b32 m0, s0
	ds_read_b128 v[158:161], v237 offset:49152
	ds_read_b128 v[170:173], v237 offset:50176
	ds_read_b128 v[174:177], v237 offset:51200
	ds_read_b128 v[178:181], v237 offset:52224
	ds_read_b128 v[182:185], v237 offset:53248
	ds_read_b128 v[186:189], v237 offset:54272
	ds_read_b128 v[210:213], v237 offset:55296
	ds_read_b128 v[214:217], v237 offset:56320
	global_load_lds_dwordx4 v[218:219], off
	s_add_i32 m0, s0, 0x2000
	s_add_u32 s0, s70, 0x160080
	v_lshl_add_u64 v[218:219], v[220:221], 0, s[82:83]
	s_addc_u32 s1, s71, 0
	s_add_i32 s8, s9, s28
	global_load_lds_dwordx4 v[218:219], off
	v_lshl_add_u64 v[218:219], s[0:1], 0, v[192:193]
	s_mov_b32 m0, s8
	s_nop 0
	global_load_lds_dwordx4 v[218:219], off
	v_lshl_add_u64 v[218:219], s[0:1], 0, v[190:191]
	s_add_i32 m0, s8, 0x2000
	s_nop 0
	global_load_lds_dwordx4 v[218:219], off
	v_lshl_add_u64 v[218:219], v[222:223], 0, s[82:83]
	s_mov_b32 m0, s68
	s_nop 0
	global_load_lds_dwordx4 v[218:219], off
	v_lshl_add_u64 v[218:219], v[224:225], 0, s[82:83]
	s_mov_b32 m0, s79
	s_nop 0
	global_load_lds_dwordx4 v[218:219], off
	s_waitcnt vmcnt(8)
	s_waitcnt lgkmcnt(0)
	s_barrier
	s_setprio 1
	s_waitcnt lgkmcnt(0)
	v_mfma_f32_16x16x32_bf16 v[62:65], v[70:73], v[158:161], v[62:65]
	v_mfma_f32_16x16x32_bf16 v[62:65], v[82:85], v[170:173], v[62:65]
	v_mfma_f32_16x16x32_bf16 v[58:61], v[106:109], v[170:173], v[58:61]
	v_mfma_f32_16x16x32_bf16 v[58:61], v[94:97], v[158:161], v[58:61]
	v_mfma_f32_16x16x32_bf16 v[54:57], v[118:121], v[158:161], v[54:57]
	v_mfma_f32_16x16x32_bf16 v[54:57], v[130:133], v[170:173], v[54:57]
	v_mfma_f32_16x16x32_bf16 v[50:53], v[154:157], v[170:173], v[50:53]
	v_mfma_f32_16x16x32_bf16 v[50:53], v[142:145], v[158:161], v[50:53]
	v_mfma_f32_16x16x32_bf16 v[34:37], v[142:145], v[174:177], v[34:37]
	v_mfma_f32_16x16x32_bf16 v[34:37], v[154:157], v[178:181], v[34:37]
	v_mfma_f32_16x16x32_bf16 v[38:41], v[130:133], v[178:181], v[38:41]
	v_mfma_f32_16x16x32_bf16 v[38:41], v[118:121], v[174:177], v[38:41]
	v_mfma_f32_16x16x32_bf16 v[42:45], v[94:97], v[174:177], v[42:45]
	v_mfma_f32_16x16x32_bf16 v[42:45], v[106:109], v[178:181], v[42:45]
	v_mfma_f32_16x16x32_bf16 v[46:49], v[82:85], v[178:181], v[46:49]
	v_mfma_f32_16x16x32_bf16 v[46:49], v[70:73], v[174:177], v[46:49]
	v_mfma_f32_16x16x32_bf16 v[30:33], v[70:73], v[182:185], v[30:33]
	v_mfma_f32_16x16x32_bf16 v[30:33], v[82:85], v[186:189], v[30:33]
	v_mfma_f32_16x16x32_bf16 v[26:29], v[106:109], v[186:189], v[26:29]
	v_mfma_f32_16x16x32_bf16 v[26:29], v[94:97], v[182:185], v[26:29]
	v_mfma_f32_16x16x32_bf16 v[22:25], v[118:121], v[182:185], v[22:25]
	v_mfma_f32_16x16x32_bf16 v[22:25], v[130:133], v[186:189], v[22:25]
	v_mfma_f32_16x16x32_bf16 v[18:21], v[154:157], v[186:189], v[18:21]
	v_mfma_f32_16x16x32_bf16 v[18:21], v[142:145], v[182:185], v[18:21]
	v_mfma_f32_16x16x32_bf16 v[2:5], v[142:145], v[210:213], v[2:5]
	v_mfma_f32_16x16x32_bf16 v[2:5], v[154:157], v[214:217], v[2:5]
	v_mfma_f32_16x16x32_bf16 v[6:9], v[130:133], v[214:217], v[6:9]
	v_mfma_f32_16x16x32_bf16 v[6:9], v[118:121], v[210:213], v[6:9]
	v_mfma_f32_16x16x32_bf16 v[10:13], v[94:97], v[210:213], v[10:13]
	v_mfma_f32_16x16x32_bf16 v[10:13], v[106:109], v[214:217], v[10:13]
	v_mfma_f32_16x16x32_bf16 v[14:17], v[82:85], v[214:217], v[14:17]
	v_mfma_f32_16x16x32_bf16 v[14:17], v[70:73], v[210:213], v[14:17]
	s_setprio 0
	s_barrier
	s_add_i32 s41, s41, 2
	s_add_u32 s7, s7, 0x100
	s_addc_u32 s23, s23, 0
	s_cmpk_gt_u32 s41, 0x55
	s_mov_b64 s[8:9], s[64:65]
	s_cbranch_scc1 .LBB0_648
